# hand-written FFN-up prompt epilogue: conv row shifts folded into DPP FMAs, packed f32 gelu gating, boundary rows stored while the conv weights load
# speedup vs baseline: 1.0160x; 1.0160x over previous
; #define PG8_STAGE(bufoff, gbase, voff) do { _Pragma("unroll") for (int _i = 0; _i < 2; ++_i) \
;         __builtin_amdgcn_global_load_lds((const unsigned*)((const char*)(gbase) + (voff)[_i]), (LAS unsigned*)(lds + (bufoff) + ldsw + _i * 8192), 16, 0, 0); } while (0)
; #define PG8_LDA(dst, b, h) do { _Pragma("unroll") for (int m = 0; m < 4; ++m) _Pragma("unroll") for (int k = 0; k < 2; ++k) dst[m][k] = *(const LAS bf16x8*)(lds + PG8_SA(b, h) + aoff + m * 2048 + k * 1024); } while (0)
; #define PG8_LDB(dst, b, h) do { _Pragma("unroll") for (int n = 0; n < 2; ++n) _Pragma("unroll") for (int k = 0; k < 2; ++k) dst[n][k] = *(const LAS bf16x8*)(lds + PG8_SB(b, h) + boff + n * 2048 + k * 1024); } while (0)
; #define PG8_MMA(ai, bj, At, Bt) do { __builtin_amdgcn_s_setprio(1); _Pragma("unroll") for (int m = 0; m < 4; ++m) _Pragma("unroll") for (int n = 0; n < 2; ++n) _Pragma("unroll") for (int k = 0; k < 2; ++k) \
;         acc[ai][bj][m][n] = __builtin_amdgcn_mfma_f32_16x16x32_bf16(Bt[n][k], At[m][k], acc[ai][bj][m][n], 0, 0, 0); __builtin_amdgcn_s_setprio(0); } while (0)
; #define PG8_WAIT_V(n) asm volatile("s_waitcnt vmcnt(" #n ")" ::: "memory")
; #define PG8_WAIT_L(n) asm volatile("s_waitcnt lgkmcnt(" #n ")" ::: "memory")
; template <class Epi, class S_t>
; __device__ __forceinline__ void gemm_phase(LAS unsigned char* lds, int lda, int ldb, const S_t& S, const Epi& E) {
;     ...
;         for (int t = 0; t < nt; t += 2) {
;             const bool last = (t == nt - 2);
;             const char* a1 = cA + (size_t)(t + 1) * kstep;
;             const char* a2 = last ? nA : cA + (size_t)(t + 2) * kstep; const char* b2 = last ? nB : cB + (size_t)(t + 2) * kstep;
;             const char* a3 = a2 + kstep; const char* b3 = b2 + kstep;
;             PG8_LDB(B0, 0, 0); PG8_SCHED; PG8_LDA(At, 0, 0); PG8_STAGE(PG8_SA(1, 1), a1 + hstepA, voffA);
;             PG8_WAIT_L(8); PG8_BAR; PG8_WAIT_L(0); PG8_MMA(0, 0, At, B0); PG8_BAR; PG8_SCHED;
;             PG8_LDB(B1, 0, 1); PG8_STAGE(PG8_SB(0, 0), b2, voffB);
;             PG8_BAR; PG8_WAIT_L(0); PG8_MMA(0, 1, At, B1); PG8_BAR;
;             PG8_LDA(At, 0, 1); PG8_STAGE(PG8_SA(0, 0), a2, voffA);
;             PG8_BAR; PG8_WAIT_L(0); PG8_MMA(1, 0, At, B0); PG8_BAR; PG8_SCHED;
;             PG8_STAGE(PG8_SB(0, 1), b2 + hstepB, voffB);
;             PG8_WAIT_V(6); PG8_BAR; PG8_MMA(1, 1, At, B1); PG8_BAR;
.LBB0_1200:
	ds_read_b128 v[128:131], v223
	ds_read_b128 v[132:135], v223 offset:1024
	ds_read_b128 v[136:139], v223 offset:2048
	ds_read_b128 v[140:143], v223 offset:3072
	s_add_u32 s33, s74, 0xfff80080
	s_addc_u32 s43, s75, -1
	s_cmp_eq_u32 s5, 28
	s_cselect_b32 s79, s69, s43
	s_cselect_b32 s78, s68, s33
	s_cselect_b32 s77, s71, s1
	s_cselect_b32 s76, s70, s0
	s_add_i32 m0, s7, 0xc000
	ds_read_b128 v[144:147], v246
	ds_read_b128 v[148:151], v246 offset:1024
	ds_read_b128 v[152:155], v246 offset:2048
	ds_read_b128 v[156:159], v246 offset:3072
	ds_read_b128 v[160:163], v246 offset:4096
	ds_read_b128 v[164:167], v246 offset:5120
	ds_read_b128 v[168:171], v246 offset:6144
	ds_read_b128 v[172:175], v246 offset:7168
	global_load_lds_dwordx4 v236, s[74:75]
	s_add_i32 m0, s7, 0xe000
	s_nop 0
	global_load_lds_dwordx4 v238, s[74:75]
	s_waitcnt lgkmcnt(8)
	s_barrier
	s_waitcnt lgkmcnt(0)
	s_setprio 1
	s_waitcnt lgkmcnt(0)
	v_mfma_f32_16x16x32_bf16 v[124:127], v[128:131], v[144:147], v[124:127]
	v_mfma_f32_16x16x32_bf16 v[120:123], v[136:139], v[144:147], v[120:123]
	v_mfma_f32_16x16x32_bf16 v[116:119], v[128:131], v[152:155], v[116:119]
	v_mfma_f32_16x16x32_bf16 v[108:111], v[136:139], v[152:155], v[108:111]
	v_mfma_f32_16x16x32_bf16 v[100:103], v[128:131], v[160:163], v[100:103]
	v_mfma_f32_16x16x32_bf16 v[92:95], v[136:139], v[160:163], v[92:95]
	v_mfma_f32_16x16x32_bf16 v[84:87], v[128:131], v[168:171], v[84:87]
	v_mfma_f32_16x16x32_bf16 v[76:79], v[136:139], v[168:171], v[76:79]
	v_mfma_f32_16x16x32_bf16 v[124:127], v[132:135], v[148:151], v[124:127]
	v_mfma_f32_16x16x32_bf16 v[120:123], v[140:143], v[148:151], v[120:123]
	v_mfma_f32_16x16x32_bf16 v[116:119], v[132:135], v[156:159], v[116:119]
	v_mfma_f32_16x16x32_bf16 v[108:111], v[140:143], v[156:159], v[108:111]
	v_mfma_f32_16x16x32_bf16 v[100:103], v[132:135], v[164:167], v[100:103]
	v_mfma_f32_16x16x32_bf16 v[92:95], v[140:143], v[164:167], v[92:95]
	v_mfma_f32_16x16x32_bf16 v[84:87], v[132:135], v[172:175], v[84:87]
	v_mfma_f32_16x16x32_bf16 v[76:79], v[140:143], v[172:175], v[76:79]
	s_setprio 0
	s_barrier
	s_add_i32 s33, s88, s64
	s_add_u32 s98, s76, s38
	s_addc_u32 s99, s77, s39
	s_mov_b32 m0, s33
	ds_read_b128 v[176:179], v247
	ds_read_b128 v[180:183], v247 offset:1024
	ds_read_b128 v[184:187], v247 offset:2048
	ds_read_b128 v[188:191], v247 offset:3072
	global_load_lds_dwordx4 v228, s[76:77]
	s_add_i32 m0, s33, 0x2000
	s_nop 0
	global_load_lds_dwordx4 v224, s[76:77]
	s_barrier
	s_waitcnt lgkmcnt(0)
	s_setprio 1
	s_waitcnt lgkmcnt(0)
	v_mfma_f32_16x16x32_bf16 v[112:115], v[176:179], v[144:147], v[112:115]
	v_mfma_f32_16x16x32_bf16 v[104:107], v[184:187], v[144:147], v[104:107]
	v_mfma_f32_16x16x32_bf16 v[96:99], v[176:179], v[152:155], v[96:99]
	v_mfma_f32_16x16x32_bf16 v[88:91], v[184:187], v[152:155], v[88:91]
	v_mfma_f32_16x16x32_bf16 v[80:83], v[176:179], v[160:163], v[80:83]
	v_mfma_f32_16x16x32_bf16 v[72:75], v[184:187], v[160:163], v[72:75]
	v_mfma_f32_16x16x32_bf16 v[68:71], v[176:179], v[168:171], v[68:71]
	v_mfma_f32_16x16x32_bf16 v[64:67], v[184:187], v[168:171], v[64:67]
	v_mfma_f32_16x16x32_bf16 v[112:115], v[180:183], v[148:151], v[112:115]
	v_mfma_f32_16x16x32_bf16 v[104:107], v[188:191], v[148:151], v[104:107]
	v_mfma_f32_16x16x32_bf16 v[96:99], v[180:183], v[156:159], v[96:99]
	v_mfma_f32_16x16x32_bf16 v[88:91], v[188:191], v[156:159], v[88:91]
	v_mfma_f32_16x16x32_bf16 v[80:83], v[180:183], v[164:167], v[80:83]
	v_mfma_f32_16x16x32_bf16 v[72:75], v[188:191], v[164:167], v[72:75]
	v_mfma_f32_16x16x32_bf16 v[68:71], v[180:183], v[172:175], v[68:71]
	v_mfma_f32_16x16x32_bf16 v[64:67], v[188:191], v[172:175], v[64:67]
	s_setprio 0
	s_mov_b32 m0, s7
	s_add_u32 s100, s78, s38
	s_addc_u32 s101, s79, s39
	s_barrier
	ds_read_b128 v[144:147], v246 offset:16384
	ds_read_b128 v[148:151], v246 offset:17408
	ds_read_b128 v[152:155], v246 offset:18432
	ds_read_b128 v[156:159], v246 offset:19456
	ds_read_b128 v[160:163], v246 offset:20480
	ds_read_b128 v[164:167], v246 offset:21504
	ds_read_b128 v[168:171], v246 offset:22528
	ds_read_b128 v[172:175], v246 offset:23552
	global_load_lds_dwordx4 v230, s[78:79]
	s_mov_b32 m0, s35
	s_nop 0
	global_load_lds_dwordx4 v226, s[78:79]
	s_barrier
	s_waitcnt lgkmcnt(0)
	s_setprio 1
	s_waitcnt lgkmcnt(0)
	v_mfma_f32_16x16x32_bf16 v[60:63], v[128:131], v[144:147], v[60:63]
	v_mfma_f32_16x16x32_bf16 v[56:59], v[136:139], v[144:147], v[56:59]
	v_mfma_f32_16x16x32_bf16 v[52:55], v[128:131], v[152:155], v[52:55]
	v_mfma_f32_16x16x32_bf16 v[44:47], v[136:139], v[152:155], v[44:47]
	v_mfma_f32_16x16x32_bf16 v[36:39], v[128:131], v[160:163], v[36:39]
	v_mfma_f32_16x16x32_bf16 v[28:31], v[136:139], v[160:163], v[28:31]
	v_mfma_f32_16x16x32_bf16 v[20:23], v[128:131], v[168:171], v[20:23]
	v_mfma_f32_16x16x32_bf16 v[12:15], v[136:139], v[168:171], v[12:15]
	v_mfma_f32_16x16x32_bf16 v[60:63], v[132:135], v[148:151], v[60:63]
	v_mfma_f32_16x16x32_bf16 v[56:59], v[140:143], v[148:151], v[56:59]
	v_mfma_f32_16x16x32_bf16 v[52:55], v[132:135], v[156:159], v[52:55]
	v_mfma_f32_16x16x32_bf16 v[44:47], v[140:143], v[156:159], v[44:47]
	v_mfma_f32_16x16x32_bf16 v[36:39], v[132:135], v[164:167], v[36:39]
	v_mfma_f32_16x16x32_bf16 v[28:31], v[140:143], v[164:167], v[28:31]
	v_mfma_f32_16x16x32_bf16 v[20:23], v[132:135], v[172:175], v[20:23]
	v_mfma_f32_16x16x32_bf16 v[12:15], v[140:143], v[172:175], v[12:15]
	s_setprio 0
	s_barrier
	s_add_u32 s52, s76, 0x80000
	s_addc_u32 s53, s77, 0
	s_add_i32 s33, s89, s64
	s_mov_b32 m0, s33
	s_nop 0
	global_load_lds_dwordx4 v228, s[52:53]
	s_add_i32 m0, s33, 0x2000
	s_nop 0
	global_load_lds_dwordx4 v224, s[52:53]
	s_waitcnt vmcnt(6)
	s_barrier
; #define PG8_STAGE(bufoff, gbase, voff) do { _Pragma("unroll") for (int _i = 0; _i < 2; ++_i) \
;         __builtin_amdgcn_global_load_lds((const unsigned*)((const char*)(gbase) + (voff)[_i]), (LAS unsigned*)(lds + (bufoff) + ldsw + _i * 8192), 16, 0, 0); } while (0)
; #define PG8_LDA(dst, b, h) do { _Pragma("unroll") for (int m = 0; m < 4; ++m) _Pragma("unroll") for (int k = 0; k < 2; ++k) dst[m][k] = *(const LAS bf16x8*)(lds + PG8_SA(b, h) + aoff + m * 2048 + k * 1024); } while (0)
; #define PG8_LDB(dst, b, h) do { _Pragma("unroll") for (int n = 0; n < 2; ++n) _Pragma("unroll") for (int k = 0; k < 2; ++k) dst[n][k] = *(const LAS bf16x8*)(lds + PG8_SB(b, h) + boff + n * 2048 + k * 1024); } while (0)
; #define PG8_MMA(ai, bj, At, Bt) do { __builtin_amdgcn_s_setprio(1); _Pragma("unroll") for (int m = 0; m < 4; ++m) _Pragma("unroll") for (int n = 0; n < 2; ++n) _Pragma("unroll") for (int k = 0; k < 2; ++k) \
;         acc[ai][bj][m][n] = __builtin_amdgcn_mfma_f32_16x16x32_bf16(Bt[n][k], At[m][k], acc[ai][bj][m][n], 0, 0, 0); __builtin_amdgcn_s_setprio(0); } while (0)
; #define PG8_WAIT_V(n) asm volatile("s_waitcnt vmcnt(" #n ")" ::: "memory")
; #define PG8_WAIT_L(n) asm volatile("s_waitcnt lgkmcnt(" #n ")" ::: "memory")
; template <class Epi, class S_t>
; __device__ __forceinline__ void gemm_phase(LAS unsigned char* lds, int lda, int ldb, const S_t& S, const Epi& E) {
;     ...
;             PG8_BAR; PG8_WAIT_L(0); PG8_MMA(0, 1, At, B1); PG8_BAR;
;             PG8_LDA(At, 0, 1); PG8_STAGE(PG8_SA(0, 0), a2, voffA);
;             PG8_BAR; PG8_WAIT_L(0); PG8_MMA(1, 0, At, B0); PG8_BAR; PG8_SCHED;
;             PG8_STAGE(PG8_SB(0, 1), b2 + hstepB, voffB);
;             PG8_WAIT_V(6); PG8_BAR; PG8_MMA(1, 1, At, B1); PG8_BAR;
;             PG8_LDB(B0, 1, 0); PG8_SCHED; PG8_LDA(At, 1, 0); PG8_STAGE(PG8_SA(0, 1), a2 + hstepA, voffA);
;             PG8_WAIT_L(8); PG8_BAR; PG8_WAIT_L(0); PG8_MMA(0, 0, At, B0); PG8_BAR; PG8_SCHED;
;             PG8_LDB(B1, 1, 1); PG8_STAGE(PG8_SB(1, 0), b3, voffB);
;             PG8_BAR; PG8_WAIT_L(0); PG8_MMA(0, 1, At, B1); PG8_BAR;
;             PG8_LDA(At, 1, 1); PG8_STAGE(PG8_SA(1, 0), a3, voffA);
;             PG8_BAR; PG8_WAIT_L(0); PG8_MMA(1, 0, At, B0); PG8_BAR; PG8_SCHED;
;             PG8_STAGE(PG8_SB(1, 1), b3 + hstepB, voffB);
;             PG8_WAIT_V(6); PG8_BAR; PG8_MMA(1, 1, At, B1); PG8_BAR;
	s_setprio 1
	v_mfma_f32_16x16x32_bf16 v[48:51], v[176:179], v[144:147], v[48:51]
	v_mfma_f32_16x16x32_bf16 v[40:43], v[184:187], v[144:147], v[40:43]
	v_mfma_f32_16x16x32_bf16 v[32:35], v[176:179], v[152:155], v[32:35]
	v_mfma_f32_16x16x32_bf16 v[24:27], v[184:187], v[152:155], v[24:27]
	v_mfma_f32_16x16x32_bf16 v[16:19], v[176:179], v[160:163], v[16:19]
	v_mfma_f32_16x16x32_bf16 v[8:11], v[184:187], v[160:163], v[8:11]
	v_mfma_f32_16x16x32_bf16 v[4:7], v[176:179], v[168:171], v[4:7]
	v_mfma_f32_16x16x32_bf16 v[0:3], v[184:187], v[168:171], v[0:3]
	v_mfma_f32_16x16x32_bf16 v[48:51], v[180:183], v[148:151], v[48:51]
	v_mfma_f32_16x16x32_bf16 v[40:43], v[188:191], v[148:151], v[40:43]
	v_mfma_f32_16x16x32_bf16 v[32:35], v[180:183], v[156:159], v[32:35]
	v_mfma_f32_16x16x32_bf16 v[24:27], v[188:191], v[156:159], v[24:27]
	v_mfma_f32_16x16x32_bf16 v[16:19], v[180:183], v[164:167], v[16:19]
	v_mfma_f32_16x16x32_bf16 v[8:11], v[188:191], v[164:167], v[8:11]
	v_mfma_f32_16x16x32_bf16 v[4:7], v[180:183], v[172:175], v[4:7]
	v_mfma_f32_16x16x32_bf16 v[0:3], v[188:191], v[172:175], v[0:3]
	s_setprio 0
	v_add_u32_e32 v140, s90, v215
	s_barrier
	ds_read_b128 v[128:131], v140
	ds_read_b128 v[132:135], v140 offset:1024
	ds_read_b128 v[136:139], v140 offset:2048
	ds_read_b128 v[140:143], v140 offset:3072
	s_add_u32 s52, s78, 0x80000
	s_addc_u32 s53, s79, 0
	s_mov_b32 m0, s92
	ds_read_b128 v[144:147], v246 offset:32768
	ds_read_b128 v[148:151], v246 offset:33792
	ds_read_b128 v[152:155], v246 offset:34816
	ds_read_b128 v[156:159], v246 offset:35840
	ds_read_b128 v[160:163], v246 offset:36864
	ds_read_b128 v[164:167], v246 offset:37888
	ds_read_b128 v[168:171], v246 offset:38912
	ds_read_b128 v[172:175], v246 offset:39936
	global_load_lds_dwordx4 v230, s[52:53]
	s_mov_b32 m0, s50
	s_nop 0
	global_load_lds_dwordx4 v226, s[52:53]
	s_waitcnt lgkmcnt(8)
	s_barrier
	s_waitcnt lgkmcnt(0)
	s_setprio 1
	s_waitcnt lgkmcnt(0)
	v_mfma_f32_16x16x32_bf16 v[124:127], v[128:131], v[144:147], v[124:127]
	v_mfma_f32_16x16x32_bf16 v[120:123], v[136:139], v[144:147], v[120:123]
	v_mfma_f32_16x16x32_bf16 v[116:119], v[128:131], v[152:155], v[116:119]
	v_mfma_f32_16x16x32_bf16 v[108:111], v[136:139], v[152:155], v[108:111]
	v_mfma_f32_16x16x32_bf16 v[100:103], v[128:131], v[160:163], v[100:103]
	v_mfma_f32_16x16x32_bf16 v[92:95], v[136:139], v[160:163], v[92:95]
	v_mfma_f32_16x16x32_bf16 v[84:87], v[128:131], v[168:171], v[84:87]
	v_mfma_f32_16x16x32_bf16 v[76:79], v[136:139], v[168:171], v[76:79]
	v_mfma_f32_16x16x32_bf16 v[124:127], v[132:135], v[148:151], v[124:127]
	v_mfma_f32_16x16x32_bf16 v[120:123], v[140:143], v[148:151], v[120:123]
	v_mfma_f32_16x16x32_bf16 v[116:119], v[132:135], v[156:159], v[116:119]
	v_mfma_f32_16x16x32_bf16 v[108:111], v[140:143], v[156:159], v[108:111]
	v_mfma_f32_16x16x32_bf16 v[100:103], v[132:135], v[164:167], v[100:103]
	v_mfma_f32_16x16x32_bf16 v[92:95], v[140:143], v[164:167], v[92:95]
	v_mfma_f32_16x16x32_bf16 v[84:87], v[132:135], v[172:175], v[84:87]
	v_mfma_f32_16x16x32_bf16 v[76:79], v[140:143], v[172:175], v[76:79]
	s_setprio 0
	s_barrier
	s_add_i32 s33, s90, s64
	v_add_u32_e32 v188, s91, v215
	s_mov_b32 m0, s33
	ds_read_b128 v[176:179], v188
	ds_read_b128 v[180:183], v188 offset:1024
	ds_read_b128 v[184:187], v188 offset:2048
	ds_read_b128 v[188:191], v188 offset:3072
	global_load_lds_dwordx4 v228, s[98:99]
	s_add_i32 m0, s33, 0x2000
	s_nop 0
	global_load_lds_dwordx4 v224, s[98:99]
	s_barrier
	s_waitcnt lgkmcnt(0)
	s_setprio 1
	s_waitcnt lgkmcnt(0)
	v_mfma_f32_16x16x32_bf16 v[112:115], v[176:179], v[144:147], v[112:115]
	v_mfma_f32_16x16x32_bf16 v[104:107], v[184:187], v[144:147], v[104:107]
	v_mfma_f32_16x16x32_bf16 v[96:99], v[176:179], v[152:155], v[96:99]
	v_mfma_f32_16x16x32_bf16 v[88:91], v[184:187], v[152:155], v[88:91]
	v_mfma_f32_16x16x32_bf16 v[80:83], v[176:179], v[160:163], v[80:83]
	v_mfma_f32_16x16x32_bf16 v[72:75], v[184:187], v[160:163], v[72:75]
	v_mfma_f32_16x16x32_bf16 v[68:71], v[176:179], v[168:171], v[68:71]
	v_mfma_f32_16x16x32_bf16 v[64:67], v[184:187], v[168:171], v[64:67]
	v_mfma_f32_16x16x32_bf16 v[112:115], v[180:183], v[148:151], v[112:115]
	v_mfma_f32_16x16x32_bf16 v[104:107], v[188:191], v[148:151], v[104:107]
	v_mfma_f32_16x16x32_bf16 v[96:99], v[180:183], v[156:159], v[96:99]
	v_mfma_f32_16x16x32_bf16 v[88:91], v[188:191], v[156:159], v[88:91]
	v_mfma_f32_16x16x32_bf16 v[80:83], v[180:183], v[164:167], v[80:83]
	v_mfma_f32_16x16x32_bf16 v[72:75], v[188:191], v[164:167], v[72:75]
	v_mfma_f32_16x16x32_bf16 v[68:71], v[180:183], v[172:175], v[68:71]
	v_mfma_f32_16x16x32_bf16 v[64:67], v[188:191], v[172:175], v[64:67]
	s_setprio 0
	s_mov_b32 m0, s96
	s_barrier
	ds_read_b128 v[144:147], v246 offset:49152
	ds_read_b128 v[148:151], v246 offset:50176
	ds_read_b128 v[152:155], v246 offset:51200
	ds_read_b128 v[156:159], v246 offset:52224
	ds_read_b128 v[160:163], v246 offset:53248
	ds_read_b128 v[164:167], v246 offset:54272
	ds_read_b128 v[168:171], v246 offset:55296
	ds_read_b128 v[172:175], v246 offset:56320
	global_load_lds_dwordx4 v230, s[100:101]
	s_mov_b32 m0, s97
	s_nop 0
	global_load_lds_dwordx4 v226, s[100:101]
	s_barrier
; template <class Epi, class S_t>
; __device__ __forceinline__ void gemm_phase(LAS unsigned char* lds, int lda, int ldb, const S_t& S, const Epi& E) {
;     ...
;             PG8_BAR; PG8_WAIT_L(0); PG8_MMA(0, 1, At, B1); PG8_BAR;
;             PG8_LDA(At, 1, 1); PG8_STAGE(PG8_SA(1, 0), a3, voffA);
;             PG8_BAR; PG8_WAIT_L(0); PG8_MMA(1, 0, At, B0); PG8_BAR; PG8_SCHED;
;             PG8_STAGE(PG8_SB(1, 1), b3 + hstepB, voffB);
;             PG8_WAIT_V(6); PG8_BAR; PG8_MMA(1, 1, At, B1); PG8_BAR;
;         }
;         E(acc, cur, wr, wc, fr, fq);
;     __device__ __forceinline__ void operator()(const f32x4 (&acc)[2][2][4][2], const Unit& u, int wr, int wc, int fr, int fq) const {
;     ...
;         const int j0 = u.pn * HALF + wc * 32 + 8 * fq;
;         u32x2 res0[8];
; #pragma unroll
;         for (int n = 0; n < 2; ++n) {
;             asm volatile("" ::: "memory");
;             const int jc = j0 + 4 * n;
;             const f32x4 wg0 = *(const f32x4*)(wconv + jc), wg1 = *(const f32x4*)(wconv + 2 * DFF + jc), wg2 = *(const f32x4*)(wconv + 4 * DFF + jc), bg = *(const f32x4*)(bconv + jc);
;             const f32x4 wv0 = *(const f32x4*)(wconv + DFF + jc), wv1 = *(const f32x4*)(wconv + 3 * DFF + jc), wv2 = *(const f32x4*)(wconv + 5 * DFF + jc), bv = *(const f32x4*)(bconv + DFF + jc);
; #pragma unroll
;             for (int ai = 0; ai < 2; ++ai)
; #pragma unroll
;                 for (int m = 0; m < 4; ++m) { const int row = row0 + ai * HALF + m * 16;
;                     const f32x4 g0 = acc[ai][0][m][n], v0 = acc[ai][1][m][n];
;                     f32x4 gp = (f32x4){0.f, 0.f, 0.f, 0.f}, vp = gp;
;                     if (m > 0) { gp = acc[ai][0][m > 0 ? m - 1 : 0][n]; vp = acc[ai][1][m > 0 ? m - 1 : 0][n]; }
;                     f32x4 f;
; #pragma unroll
;                     for (int j = 0; j < 4; ++j) {
;                         const float g1 = dpp_shr1(dpp_ror1(gp[j]), g0[j]), g2 = dpp_shr2(dpp_ror2(gp[j]), g0[j]);
;                         const float v1 = dpp_shr1(dpp_ror1(vp[j]), v0[j]), v2 = dpp_shr2(dpp_ror2(vp[j]), v0[j]);
;                         const float cg_ = bg[j] + g2 * wg0[j] + g1 * wg1[j] + g0[j] * wg2[j];
;                         const float cv_ = bv[j] + v2 * wv0[j] + v1 * wv1[j] + v0[j] * wv2[j];
;                         f[j] = gelu_tanh(cg_) * cv_; }
;                     u32x2 w; w.x = pk2(f[0], f[1]); w.y = pk2(f[2], f[3]);
	s_waitcnt lgkmcnt(0)
	s_setprio 1
	s_waitcnt lgkmcnt(0)
	v_mfma_f32_16x16x32_bf16 v[60:63], v[128:131], v[144:147], v[60:63]
	v_mfma_f32_16x16x32_bf16 v[56:59], v[136:139], v[144:147], v[56:59]
	v_mfma_f32_16x16x32_bf16 v[52:55], v[128:131], v[152:155], v[52:55]
	v_mfma_f32_16x16x32_bf16 v[44:47], v[136:139], v[152:155], v[44:47]
	v_mfma_f32_16x16x32_bf16 v[36:39], v[128:131], v[160:163], v[36:39]
	v_mfma_f32_16x16x32_bf16 v[28:31], v[136:139], v[160:163], v[28:31]
	v_mfma_f32_16x16x32_bf16 v[20:23], v[128:131], v[168:171], v[20:23]
	v_mfma_f32_16x16x32_bf16 v[12:15], v[136:139], v[168:171], v[12:15]
	v_mfma_f32_16x16x32_bf16 v[60:63], v[132:135], v[148:151], v[60:63]
	v_mfma_f32_16x16x32_bf16 v[56:59], v[140:143], v[148:151], v[56:59]
	v_mfma_f32_16x16x32_bf16 v[52:55], v[132:135], v[156:159], v[52:55]
	v_mfma_f32_16x16x32_bf16 v[44:47], v[140:143], v[156:159], v[44:47]
	v_mfma_f32_16x16x32_bf16 v[36:39], v[132:135], v[164:167], v[36:39]
	v_mfma_f32_16x16x32_bf16 v[28:31], v[140:143], v[164:167], v[28:31]
	v_mfma_f32_16x16x32_bf16 v[20:23], v[132:135], v[172:175], v[20:23]
	v_mfma_f32_16x16x32_bf16 v[12:15], v[140:143], v[172:175], v[12:15]
	s_setprio 0
	s_barrier
	s_add_u32 s52, s76, 0x80080
	s_addc_u32 s53, s77, 0
	s_add_i32 s33, s91, s64
	s_mov_b32 m0, s33
	s_nop 0
	global_load_lds_dwordx4 v228, s[52:53]
	s_add_i32 m0, s33, 0x2000
	s_nop 0
	global_load_lds_dwordx4 v224, s[52:53]
	s_waitcnt vmcnt(6)
	s_barrier
	s_setprio 1
	v_mfma_f32_16x16x32_bf16 v[48:51], v[176:179], v[144:147], v[48:51]
	v_mfma_f32_16x16x32_bf16 v[40:43], v[184:187], v[144:147], v[40:43]
	v_mfma_f32_16x16x32_bf16 v[32:35], v[176:179], v[152:155], v[32:35]
	v_mfma_f32_16x16x32_bf16 v[24:27], v[184:187], v[152:155], v[24:27]
	v_mfma_f32_16x16x32_bf16 v[16:19], v[176:179], v[160:163], v[16:19]
	v_mfma_f32_16x16x32_bf16 v[8:11], v[184:187], v[160:163], v[8:11]
	v_mfma_f32_16x16x32_bf16 v[4:7], v[176:179], v[168:171], v[4:7]
	v_mfma_f32_16x16x32_bf16 v[0:3], v[184:187], v[168:171], v[0:3]
	v_mfma_f32_16x16x32_bf16 v[48:51], v[180:183], v[148:151], v[48:51]
	v_mfma_f32_16x16x32_bf16 v[40:43], v[188:191], v[148:151], v[40:43]
	v_mfma_f32_16x16x32_bf16 v[32:35], v[180:183], v[156:159], v[32:35]
	v_mfma_f32_16x16x32_bf16 v[24:27], v[188:191], v[156:159], v[24:27]
	v_mfma_f32_16x16x32_bf16 v[16:19], v[180:183], v[164:167], v[16:19]
	v_mfma_f32_16x16x32_bf16 v[8:11], v[188:191], v[164:167], v[8:11]
	v_mfma_f32_16x16x32_bf16 v[4:7], v[180:183], v[172:175], v[4:7]
	v_mfma_f32_16x16x32_bf16 v[0:3], v[188:191], v[172:175], v[0:3]
	s_setprio 0
	s_add_i32 s5, s5, 2
	s_add_u32 s74, s74, 0x100
	s_addc_u32 s75, s75, 0
	s_add_u32 s0, s0, 0x100
	s_addc_u32 s1, s1, 0
	s_cmp_gt_u32 s5, 29
	s_barrier
	s_cbranch_scc0 .LBB0_1200
	s_lshl_b32 s5, s72, 8
	s_add_i32 s5, s5, s95
	v_or_b32_e32 v248, s5, v232
	s_cmp_lt_i32 s72, 32
	v_lshl_or_b32 v240, s42, 8, v219
	s_cbranch_scc0 .LBB0_1215
	v_lshl_or_b32 v130, s42, 7, v219
	v_readlane_b32 s16, v254, 33
	v_readlane_b32 s17, v254, 34
	v_readlane_b32 s18, v254, 35
	v_readlane_b32 s19, v254, 36
	v_readlane_b32 s20, v254, 37
	v_readlane_b32 s21, v254, 38
	v_readlane_b32 s22, v254, 39
	v_readlane_b32 s23, v254, 40
	v_readlane_b32 s24, v254, 41
	v_readlane_b32 s25, v254, 42
	v_readlane_b32 s26, v254, 43
	v_readlane_b32 s27, v254, 44
	v_readlane_b32 s28, v254, 45
	v_readlane_b32 s29, v254, 46
	v_readlane_b32 s30, v254, 47
	v_readlane_b32 s31, v254, 48
	v_ashrrev_i32_e32 v131, 31, v130
	s_ashr_i32 s72, s5, 6
	v_lshlrev_b64 v[128:129], 2, v[130:131]
	s_lshl_b32 s72, s72, 2
	s_add_i32 s73, s72, 8
	v_lshl_add_u64 v[132:133], s[26:27], 0, v[128:129]
	global_load_dwordx4 v[146:149], v[132:133], off
	global_load_dwordx4 v[178:181], v[132:133], off offset:16
	v_lshl_add_u64 v[134:135], s[58:59], 0, v[128:129]
	global_load_dwordx4 v[158:161], v[134:135], off
	global_load_dwordx4 v[190:193], v[134:135], off offset:16
	v_lshl_add_u64 v[136:137], s[46:47], 0, v[128:129]
	global_load_dwordx4 v[162:165], v[136:137], off
	global_load_dwordx4 v[194:197], v[136:137], off offset:16
	v_lshl_add_u64 v[132:133], s[48:49], 0, v[128:129]
	global_load_dwordx4 v[174:177], v[132:133], off
	global_load_dwordx4 v[206:209], v[132:133], off offset:16
	v_lshl_add_u64 v[134:135], s[60:61], 0, v[128:129]
	global_load_dwordx4 v[154:157], v[134:135], off
	global_load_dwordx4 v[186:189], v[134:135], off offset:16
	v_lshl_add_u64 v[136:137], s[54:55], 0, v[128:129]
	global_load_dwordx4 v[170:173], v[136:137], off
	global_load_dwordx4 v[202:205], v[136:137], off offset:16
	v_lshl_add_u64 v[132:133], s[24:25], 0, v[128:129]
	global_load_dwordx4 v[150:153], v[132:133], off
	global_load_dwordx4 v[182:185], v[132:133], off offset:16
	v_lshl_add_u64 v[134:135], s[56:57], 0, v[128:129]
	global_load_dwordx4 v[166:169], v[134:135], off
	global_load_dwordx4 v[198:201], v[134:135], off offset:16
	v_lshl_add_u64 v[242:243], v[130:131], 1, s[40:41]
	v_ashrrev_i32_e32 v241, 31, v240
	s_mov_b32 s98, 0xbdd2d3e8
	s_mov_b32 s99, 0xbdd2d3e8
	s_mov_b32 s100, 1.0
	s_mov_b32 s101, 1.0
	v_mov_b32_e32 v244, 0xc0135761
	v_mov_b32_e32 v245, 0xc0135761
	s_and_saveexec_b64 s[42:43], s[10:11]
	v_or_b32_e32 v144, s72, v232
	v_mov_b64_e32 v[128:129], s[80:81]
	v_mad_u64_u32 v[128:129], vcc, v144, s83, v[128:129]
	v_lshl_add_u64 v[128:129], v[240:241], 1, v[128:129]
	v_cvt_pk_bf16_f32 v132, v124, v125
	v_cvt_pk_bf16_f32 v133, v126, v127
	v_cvt_pk_bf16_f32 v134, v120, v121
	v_cvt_pk_bf16_f32 v135, v122, v123
	v_cvt_pk_bf16_f32 v136, v112, v113
	v_cvt_pk_bf16_f32 v137, v114, v115
	v_cvt_pk_bf16_f32 v138, v104, v105
	v_cvt_pk_bf16_f32 v139, v106, v107
	global_store_dwordx4 v[128:129], v[132:135], off
	global_store_dwordx4 v[128:129], v[136:139], off offset:256
	v_or_b32_e32 v144, s73, v232
	v_mov_b64_e32 v[130:131], s[80:81]
	v_mad_u64_u32 v[130:131], vcc, v144, s83, v[130:131]
	v_lshl_add_u64 v[130:131], v[240:241], 1, v[130:131]
	v_cvt_pk_bf16_f32 v140, v60, v61
	v_cvt_pk_bf16_f32 v141, v62, v63
	v_cvt_pk_bf16_f32 v142, v56, v57
	v_cvt_pk_bf16_f32 v143, v58, v59
	v_cvt_pk_bf16_f32 v250, v48, v49
	v_cvt_pk_bf16_f32 v251, v50, v51
	v_cvt_pk_bf16_f32 v252, v40, v41
	v_cvt_pk_bf16_f32 v253, v42, v43
	global_store_dwordx4 v[130:131], v[140:143], off
	global_store_dwordx4 v[130:131], v[250:253], off offset:256
	s_or_b64 exec, exec, s[42:43]
	s_and_saveexec_b64 s[42:43], s[12:13]
	v_add_u32_e32 v144, s72, v234
	v_mov_b64_e32 v[128:129], s[80:81]
	v_mad_u64_u32 v[128:129], vcc, v144, s83, v[128:129]
	v_lshl_add_u64 v[128:129], v[240:241], 1, v[128:129]
	v_cvt_pk_bf16_f32 v132, v84, v85
	v_cvt_pk_bf16_f32 v133, v86, v87
	v_cvt_pk_bf16_f32 v134, v76, v77
	v_cvt_pk_bf16_f32 v135, v78, v79
	v_cvt_pk_bf16_f32 v136, v68, v69
	v_cvt_pk_bf16_f32 v137, v70, v71
	v_cvt_pk_bf16_f32 v138, v64, v65
	v_cvt_pk_bf16_f32 v139, v66, v67
	global_store_dwordx4 v[128:129], v[132:135], off
	global_store_dwordx4 v[128:129], v[136:139], off offset:256
	s_or_b64 exec, exec, s[42:43]
	s_waitcnt vmcnt(6)
; __device__ __forceinline__ unsigned pk2(float lo, float hi) { unsigned r; asm("v_cvt_pk_bf16_f32 %0, %1, %2" : "=v"(r) : "v"(lo), "v"(hi)); return r; }
; __device__ __forceinline__ float gelu_tanh(float x) { const float y = 1.5957691216f * (x + 0.044715f * x * x * x); return x * __builtin_amdgcn_rcpf(1.0f + __expf(-y)); }
;     __device__ __forceinline__ void operator()(const f32x4 (&acc)[2][2][4][2], const Unit& u, int wr, int wc, int fr, int fq) const {
;     ...
;         for (int n = 0; n < 2; ++n) {
;             asm volatile("" ::: "memory");
;             const int jc = j0 + 4 * n;
;             const f32x4 wg0 = *(const f32x4*)(wconv + jc), wg1 = *(const f32x4*)(wconv + 2 * DFF + jc), wg2 = *(const f32x4*)(wconv + 4 * DFF + jc), bg = *(const f32x4*)(bconv + jc);
;             const f32x4 wv0 = *(const f32x4*)(wconv + DFF + jc), wv1 = *(const f32x4*)(wconv + 3 * DFF + jc), wv2 = *(const f32x4*)(wconv + 5 * DFF + jc), bv = *(const f32x4*)(bconv + DFF + jc);
; #pragma unroll
;             for (int ai = 0; ai < 2; ++ai)
; #pragma unroll
;                 for (int m = 0; m < 4; ++m) { const int row = row0 + ai * HALF + m * 16;
;                     const f32x4 g0 = acc[ai][0][m][n], v0 = acc[ai][1][m][n];
;                     f32x4 gp = (f32x4){0.f, 0.f, 0.f, 0.f}, vp = gp;
;                     if (m > 0) { gp = acc[ai][0][m > 0 ? m - 1 : 0][n]; vp = acc[ai][1][m > 0 ? m - 1 : 0][n]; }
;                     f32x4 f;
; #pragma unroll
;                     for (int j = 0; j < 4; ++j) {
;                         const float g1 = dpp_shr1(dpp_ror1(gp[j]), g0[j]), g2 = dpp_shr2(dpp_ror2(gp[j]), g0[j]);
;                         const float v1 = dpp_shr1(dpp_ror1(vp[j]), v0[j]), v2 = dpp_shr2(dpp_ror2(vp[j]), v0[j]);
;                         const float cg_ = bg[j] + g2 * wg0[j] + g1 * wg1[j] + g0[j] * wg2[j];
;                         const float cv_ = bv[j] + v2 * wv0[j] + v1 * wv1[j] + v0[j] * wv2[j];
;                         f[j] = gelu_tanh(cg_) * cv_; }
;                     u32x2 w; w.x = pk2(f[0], f[1]); w.y = pk2(f[2], f[3]);
;                     if (n == 0) res0[ai * 4 + m] = w;
;                     else if (m > 0 || fr >= 2) { u32x4 w4; w4.x = res0[ai * 4 + m].x; w4.y = res0[ai * 4 + m].y; w4.z = w.x; w4.w = w.y; *(u32x4*)(F + (size_t)row * DFF + j0) = w4; }
	s_nop 4
	v_pk_fma_f32 v[132:133], v[124:125], v[158:159], v[146:147]
	v_pk_fma_f32 v[136:137], v[112:113], v[174:175], v[162:163]
	v_pk_fma_f32 v[134:135], v[126:127], v[160:161], v[148:149]
	v_pk_fma_f32 v[138:139], v[114:115], v[176:177], v[164:165]
	v_fmac_f32_dpp v132, v124, v154 row_shr:1 row_mask:0xf bank_mask:0xf
	v_fmac_f32_dpp v133, v125, v155 row_shr:1 row_mask:0xf bank_mask:0xf
	v_fmac_f32_dpp v134, v126, v156 row_shr:1 row_mask:0xf bank_mask:0xf
	v_fmac_f32_dpp v135, v127, v157 row_shr:1 row_mask:0xf bank_mask:0xf
	v_fmac_f32_dpp v136, v112, v170 row_shr:1 row_mask:0xf bank_mask:0xf
	v_fmac_f32_dpp v137, v113, v171 row_shr:1 row_mask:0xf bank_mask:0xf
	v_fmac_f32_dpp v138, v114, v172 row_shr:1 row_mask:0xf bank_mask:0xf
	v_fmac_f32_dpp v139, v115, v173 row_shr:1 row_mask:0xf bank_mask:0xf
	v_fmac_f32_dpp v132, v124, v150 row_shr:2 row_mask:0xf bank_mask:0xf
	v_fmac_f32_dpp v133, v125, v151 row_shr:2 row_mask:0xf bank_mask:0xf
	v_fmac_f32_dpp v134, v126, v152 row_shr:2 row_mask:0xf bank_mask:0xf
	v_fmac_f32_dpp v135, v127, v153 row_shr:2 row_mask:0xf bank_mask:0xf
	v_fmac_f32_dpp v136, v112, v166 row_shr:2 row_mask:0xf bank_mask:0xf
	v_fmac_f32_dpp v137, v113, v167 row_shr:2 row_mask:0xf bank_mask:0xf
	v_fmac_f32_dpp v138, v114, v168 row_shr:2 row_mask:0xf bank_mask:0xf
	v_fmac_f32_dpp v139, v115, v169 row_shr:2 row_mask:0xf bank_mask:0xf
	v_pk_mul_f32 v[140:141], v[132:133], v[132:133]
	v_pk_mul_f32 v[142:143], v[134:135], v[134:135]
	v_pk_fma_f32 v[140:141], v[140:141], s[98:99], v[244:245]
	v_pk_fma_f32 v[142:143], v[142:143], s[98:99], v[244:245]
	v_pk_mul_f32 v[140:141], v[132:133], v[140:141]
	v_pk_mul_f32 v[142:143], v[134:135], v[142:143]
	v_exp_f32_e32 v140, v140
	v_exp_f32_e32 v141, v141
	v_exp_f32_e32 v142, v142
	v_exp_f32_e32 v143, v143
	v_pk_add_f32 v[140:141], v[140:141], s[100:101]
	v_pk_add_f32 v[142:143], v[142:143], s[100:101]
	v_rcp_f32_e32 v140, v140
	v_rcp_f32_e32 v141, v141
	v_rcp_f32_e32 v142, v142
	v_rcp_f32_e32 v143, v143
	v_pk_mul_f32 v[140:141], v[132:133], v[140:141]
	v_pk_mul_f32 v[142:143], v[134:135], v[142:143]
	v_pk_mul_f32 v[140:141], v[140:141], v[136:137]
	v_pk_mul_f32 v[142:143], v[142:143], v[138:139]
	v_cvt_pk_bf16_f32 v128, v140, v141
	v_cvt_pk_bf16_f32 v129, v142, v143
	v_pk_fma_f32 v[132:133], v[120:121], v[190:191], v[178:179]
	v_pk_fma_f32 v[136:137], v[104:105], v[206:207], v[194:195]
	v_pk_fma_f32 v[134:135], v[122:123], v[192:193], v[180:181]
	v_pk_fma_f32 v[138:139], v[106:107], v[208:209], v[196:197]
	v_fmac_f32_dpp v132, v120, v186 row_shr:1 row_mask:0xf bank_mask:0xf
	v_fmac_f32_dpp v133, v121, v187 row_shr:1 row_mask:0xf bank_mask:0xf
	v_fmac_f32_dpp v134, v122, v188 row_shr:1 row_mask:0xf bank_mask:0xf
	v_fmac_f32_dpp v135, v123, v189 row_shr:1 row_mask:0xf bank_mask:0xf
	v_fmac_f32_dpp v136, v104, v202 row_shr:1 row_mask:0xf bank_mask:0xf
	v_fmac_f32_dpp v137, v105, v203 row_shr:1 row_mask:0xf bank_mask:0xf
	v_fmac_f32_dpp v138, v106, v204 row_shr:1 row_mask:0xf bank_mask:0xf
	v_fmac_f32_dpp v139, v107, v205 row_shr:1 row_mask:0xf bank_mask:0xf
	v_fmac_f32_dpp v132, v120, v182 row_shr:2 row_mask:0xf bank_mask:0xf
	v_fmac_f32_dpp v133, v121, v183 row_shr:2 row_mask:0xf bank_mask:0xf
	v_fmac_f32_dpp v134, v122, v184 row_shr:2 row_mask:0xf bank_mask:0xf
	v_fmac_f32_dpp v135, v123, v185 row_shr:2 row_mask:0xf bank_mask:0xf
	v_fmac_f32_dpp v136, v104, v198 row_shr:2 row_mask:0xf bank_mask:0xf
	v_fmac_f32_dpp v137, v105, v199 row_shr:2 row_mask:0xf bank_mask:0xf
	v_fmac_f32_dpp v138, v106, v200 row_shr:2 row_mask:0xf bank_mask:0xf
	v_fmac_f32_dpp v139, v107, v201 row_shr:2 row_mask:0xf bank_mask:0xf
	v_pk_mul_f32 v[140:141], v[132:133], v[132:133]
	v_pk_mul_f32 v[142:143], v[134:135], v[134:135]
	v_pk_fma_f32 v[140:141], v[140:141], s[98:99], v[244:245]
	v_pk_fma_f32 v[142:143], v[142:143], s[98:99], v[244:245]
	v_pk_mul_f32 v[140:141], v[132:133], v[140:141]
	v_pk_mul_f32 v[142:143], v[134:135], v[142:143]
	v_exp_f32_e32 v140, v140
	v_exp_f32_e32 v141, v141
	v_exp_f32_e32 v142, v142
	v_exp_f32_e32 v143, v143
	v_pk_add_f32 v[140:141], v[140:141], s[100:101]
	v_pk_add_f32 v[142:143], v[142:143], s[100:101]
	v_rcp_f32_e32 v140, v140
	v_rcp_f32_e32 v141, v141
	v_rcp_f32_e32 v142, v142
	v_rcp_f32_e32 v143, v143
	v_pk_mul_f32 v[140:141], v[132:133], v[140:141]
	v_pk_mul_f32 v[142:143], v[134:135], v[142:143]
	v_pk_mul_f32 v[140:141], v[140:141], v[136:137]
	v_pk_mul_f32 v[142:143], v[142:143], v[138:139]
	v_cvt_pk_bf16_f32 v130, v140, v141
	v_cvt_pk_bf16_f32 v131, v142, v143
	s_and_saveexec_b64 s[42:43], s[8:9]
	v_mad_u64_u32 v[144:145], vcc, v248, s4, v[242:243]
	global_store_dwordx4 v[144:145], v[128:131], off
	s_or_b64 exec, exec, s[42:43]
	s_nop 4
	v_pk_fma_f32 v[132:133], v[116:117], v[158:159], v[146:147]
	v_pk_fma_f32 v[136:137], v[96:97], v[174:175], v[162:163]
	v_pk_fma_f32 v[134:135], v[118:119], v[160:161], v[148:149]
	v_pk_fma_f32 v[138:139], v[98:99], v[176:177], v[164:165]
	v_fmac_f32_dpp v132, v116, v154 row_shr:1 row_mask:0xf bank_mask:0xf
	v_fmac_f32_dpp v133, v117, v155 row_shr:1 row_mask:0xf bank_mask:0xf
	v_fmac_f32_dpp v134, v118, v156 row_shr:1 row_mask:0xf bank_mask:0xf
	v_fmac_f32_dpp v135, v119, v157 row_shr:1 row_mask:0xf bank_mask:0xf
	v_fmac_f32_dpp v136, v96, v170 row_shr:1 row_mask:0xf bank_mask:0xf
	v_fmac_f32_dpp v137, v97, v171 row_shr:1 row_mask:0xf bank_mask:0xf
	v_fmac_f32_dpp v138, v98, v172 row_shr:1 row_mask:0xf bank_mask:0xf
	v_fmac_f32_dpp v139, v99, v173 row_shr:1 row_mask:0xf bank_mask:0xf
	v_fmac_f32_dpp v132, v124, v154 row_shl:15 row_mask:0xf bank_mask:0xf
	v_fmac_f32_dpp v133, v125, v155 row_shl:15 row_mask:0xf bank_mask:0xf
; __device__ __forceinline__ unsigned pk2(float lo, float hi) { unsigned r; asm("v_cvt_pk_bf16_f32 %0, %1, %2" : "=v"(r) : "v"(lo), "v"(hi)); return r; }
; __device__ __forceinline__ float gelu_tanh(float x) { const float y = 1.5957691216f * (x + 0.044715f * x * x * x); return x * __builtin_amdgcn_rcpf(1.0f + __expf(-y)); }
;     __device__ __forceinline__ void operator()(const f32x4 (&acc)[2][2][4][2], const Unit& u, int wr, int wc, int fr, int fq) const {
;     ...
;         for (int n = 0; n < 2; ++n) {
;             asm volatile("" ::: "memory");
;             const int jc = j0 + 4 * n;
;             const f32x4 wg0 = *(const f32x4*)(wconv + jc), wg1 = *(const f32x4*)(wconv + 2 * DFF + jc), wg2 = *(const f32x4*)(wconv + 4 * DFF + jc), bg = *(const f32x4*)(bconv + jc);
;             const f32x4 wv0 = *(const f32x4*)(wconv + DFF + jc), wv1 = *(const f32x4*)(wconv + 3 * DFF + jc), wv2 = *(const f32x4*)(wconv + 5 * DFF + jc), bv = *(const f32x4*)(bconv + DFF + jc);
; #pragma unroll
;             for (int ai = 0; ai < 2; ++ai)
; #pragma unroll
;                 for (int m = 0; m < 4; ++m) { const int row = row0 + ai * HALF + m * 16;
;                     const f32x4 g0 = acc[ai][0][m][n], v0 = acc[ai][1][m][n];
;                     f32x4 gp = (f32x4){0.f, 0.f, 0.f, 0.f}, vp = gp;
;                     if (m > 0) { gp = acc[ai][0][m > 0 ? m - 1 : 0][n]; vp = acc[ai][1][m > 0 ? m - 1 : 0][n]; }
;                     f32x4 f;
; #pragma unroll
;                     for (int j = 0; j < 4; ++j) {
;                         const float g1 = dpp_shr1(dpp_ror1(gp[j]), g0[j]), g2 = dpp_shr2(dpp_ror2(gp[j]), g0[j]);
;                         const float v1 = dpp_shr1(dpp_ror1(vp[j]), v0[j]), v2 = dpp_shr2(dpp_ror2(vp[j]), v0[j]);
;                         const float cg_ = bg[j] + g2 * wg0[j] + g1 * wg1[j] + g0[j] * wg2[j];
;                         const float cv_ = bv[j] + v2 * wv0[j] + v1 * wv1[j] + v0[j] * wv2[j];
;                         f[j] = gelu_tanh(cg_) * cv_; }
;                     u32x2 w; w.x = pk2(f[0], f[1]); w.y = pk2(f[2], f[3]);
;                     if (n == 0) res0[ai * 4 + m] = w;
;                     else if (m > 0 || fr >= 2) { u32x4 w4; w4.x = res0[ai * 4 + m].x; w4.y = res0[ai * 4 + m].y; w4.z = w.x; w4.w = w.y; *(u32x4*)(F + (size_t)row * DFF + j0) = w4; }
	v_fmac_f32_dpp v134, v126, v156 row_shl:15 row_mask:0xf bank_mask:0xf
	v_fmac_f32_dpp v135, v127, v157 row_shl:15 row_mask:0xf bank_mask:0xf
	v_fmac_f32_dpp v136, v112, v170 row_shl:15 row_mask:0xf bank_mask:0xf
	v_fmac_f32_dpp v137, v113, v171 row_shl:15 row_mask:0xf bank_mask:0xf
	v_fmac_f32_dpp v138, v114, v172 row_shl:15 row_mask:0xf bank_mask:0xf
	v_fmac_f32_dpp v139, v115, v173 row_shl:15 row_mask:0xf bank_mask:0xf
	v_fmac_f32_dpp v132, v116, v150 row_shr:2 row_mask:0xf bank_mask:0xf
	v_fmac_f32_dpp v133, v117, v151 row_shr:2 row_mask:0xf bank_mask:0xf
	v_fmac_f32_dpp v134, v118, v152 row_shr:2 row_mask:0xf bank_mask:0xf
	v_fmac_f32_dpp v135, v119, v153 row_shr:2 row_mask:0xf bank_mask:0xf
	v_fmac_f32_dpp v136, v96, v166 row_shr:2 row_mask:0xf bank_mask:0xf
	v_fmac_f32_dpp v137, v97, v167 row_shr:2 row_mask:0xf bank_mask:0xf
	v_fmac_f32_dpp v138, v98, v168 row_shr:2 row_mask:0xf bank_mask:0xf
	v_fmac_f32_dpp v139, v99, v169 row_shr:2 row_mask:0xf bank_mask:0xf
	v_fmac_f32_dpp v132, v124, v150 row_shl:14 row_mask:0xf bank_mask:0xf
	v_fmac_f32_dpp v133, v125, v151 row_shl:14 row_mask:0xf bank_mask:0xf
	v_fmac_f32_dpp v134, v126, v152 row_shl:14 row_mask:0xf bank_mask:0xf
	v_fmac_f32_dpp v135, v127, v153 row_shl:14 row_mask:0xf bank_mask:0xf
	v_fmac_f32_dpp v136, v112, v166 row_shl:14 row_mask:0xf bank_mask:0xf
	v_fmac_f32_dpp v137, v113, v167 row_shl:14 row_mask:0xf bank_mask:0xf
	v_fmac_f32_dpp v138, v114, v168 row_shl:14 row_mask:0xf bank_mask:0xf
	v_fmac_f32_dpp v139, v115, v169 row_shl:14 row_mask:0xf bank_mask:0xf
	v_pk_mul_f32 v[140:141], v[132:133], v[132:133]
	v_pk_mul_f32 v[142:143], v[134:135], v[134:135]
	v_pk_fma_f32 v[140:141], v[140:141], s[98:99], v[244:245]
	v_pk_fma_f32 v[142:143], v[142:143], s[98:99], v[244:245]
	v_pk_mul_f32 v[140:141], v[132:133], v[140:141]
	v_pk_mul_f32 v[142:143], v[134:135], v[142:143]
	v_exp_f32_e32 v140, v140
	v_exp_f32_e32 v141, v141
	v_exp_f32_e32 v142, v142
	v_exp_f32_e32 v143, v143
	v_pk_add_f32 v[140:141], v[140:141], s[100:101]
	v_pk_add_f32 v[142:143], v[142:143], s[100:101]
	v_rcp_f32_e32 v140, v140
	v_rcp_f32_e32 v141, v141
	v_rcp_f32_e32 v142, v142
	v_rcp_f32_e32 v143, v143
	v_pk_mul_f32 v[140:141], v[132:133], v[140:141]
	v_pk_mul_f32 v[142:143], v[134:135], v[142:143]
	v_pk_mul_f32 v[140:141], v[140:141], v[136:137]
	v_pk_mul_f32 v[142:143], v[142:143], v[138:139]
	v_cvt_pk_bf16_f32 v250, v140, v141
	v_cvt_pk_bf16_f32 v251, v142, v143
	v_pk_fma_f32 v[132:133], v[108:109], v[190:191], v[178:179]
	v_pk_fma_f32 v[136:137], v[88:89], v[206:207], v[194:195]
	v_pk_fma_f32 v[134:135], v[110:111], v[192:193], v[180:181]
	v_pk_fma_f32 v[138:139], v[90:91], v[208:209], v[196:197]
	v_fmac_f32_dpp v132, v108, v186 row_shr:1 row_mask:0xf bank_mask:0xf
	v_fmac_f32_dpp v133, v109, v187 row_shr:1 row_mask:0xf bank_mask:0xf
	v_fmac_f32_dpp v134, v110, v188 row_shr:1 row_mask:0xf bank_mask:0xf
	v_fmac_f32_dpp v135, v111, v189 row_shr:1 row_mask:0xf bank_mask:0xf
	v_fmac_f32_dpp v136, v88, v202 row_shr:1 row_mask:0xf bank_mask:0xf
	v_fmac_f32_dpp v137, v89, v203 row_shr:1 row_mask:0xf bank_mask:0xf
	v_fmac_f32_dpp v138, v90, v204 row_shr:1 row_mask:0xf bank_mask:0xf
	v_fmac_f32_dpp v139, v91, v205 row_shr:1 row_mask:0xf bank_mask:0xf
	v_fmac_f32_dpp v132, v120, v186 row_shl:15 row_mask:0xf bank_mask:0xf
	v_fmac_f32_dpp v133, v121, v187 row_shl:15 row_mask:0xf bank_mask:0xf
	v_fmac_f32_dpp v134, v122, v188 row_shl:15 row_mask:0xf bank_mask:0xf
	v_fmac_f32_dpp v135, v123, v189 row_shl:15 row_mask:0xf bank_mask:0xf
	v_fmac_f32_dpp v136, v104, v202 row_shl:15 row_mask:0xf bank_mask:0xf
	v_fmac_f32_dpp v137, v105, v203 row_shl:15 row_mask:0xf bank_mask:0xf
	v_fmac_f32_dpp v138, v106, v204 row_shl:15 row_mask:0xf bank_mask:0xf
	v_fmac_f32_dpp v139, v107, v205 row_shl:15 row_mask:0xf bank_mask:0xf
	v_fmac_f32_dpp v132, v108, v182 row_shr:2 row_mask:0xf bank_mask:0xf
	v_fmac_f32_dpp v133, v109, v183 row_shr:2 row_mask:0xf bank_mask:0xf
	v_fmac_f32_dpp v134, v110, v184 row_shr:2 row_mask:0xf bank_mask:0xf
	v_fmac_f32_dpp v135, v111, v185 row_shr:2 row_mask:0xf bank_mask:0xf
	v_fmac_f32_dpp v136, v88, v198 row_shr:2 row_mask:0xf bank_mask:0xf
	v_fmac_f32_dpp v137, v89, v199 row_shr:2 row_mask:0xf bank_mask:0xf
	v_fmac_f32_dpp v138, v90, v200 row_shr:2 row_mask:0xf bank_mask:0xf
	v_fmac_f32_dpp v139, v91, v201 row_shr:2 row_mask:0xf bank_mask:0xf
	v_fmac_f32_dpp v132, v120, v182 row_shl:14 row_mask:0xf bank_mask:0xf
	v_fmac_f32_dpp v133, v121, v183 row_shl:14 row_mask:0xf bank_mask:0xf
	v_fmac_f32_dpp v134, v122, v184 row_shl:14 row_mask:0xf bank_mask:0xf
	v_fmac_f32_dpp v135, v123, v185 row_shl:14 row_mask:0xf bank_mask:0xf
	v_fmac_f32_dpp v136, v104, v198 row_shl:14 row_mask:0xf bank_mask:0xf
	v_fmac_f32_dpp v137, v105, v199 row_shl:14 row_mask:0xf bank_mask:0xf
	v_fmac_f32_dpp v138, v106, v200 row_shl:14 row_mask:0xf bank_mask:0xf
	v_fmac_f32_dpp v139, v107, v201 row_shl:14 row_mask:0xf bank_mask:0xf
	v_pk_mul_f32 v[140:141], v[132:133], v[132:133]
	v_pk_mul_f32 v[142:143], v[134:135], v[134:135]
	v_pk_fma_f32 v[140:141], v[140:141], s[98:99], v[244:245]
	v_pk_fma_f32 v[142:143], v[142:143], s[98:99], v[244:245]
	v_pk_mul_f32 v[140:141], v[132:133], v[140:141]
	v_pk_mul_f32 v[142:143], v[134:135], v[142:143]
	v_exp_f32_e32 v140, v140
	v_exp_f32_e32 v141, v141
	v_exp_f32_e32 v142, v142
	v_exp_f32_e32 v143, v143
	v_pk_add_f32 v[140:141], v[140:141], s[100:101]
	v_pk_add_f32 v[142:143], v[142:143], s[100:101]
	v_rcp_f32_e32 v140, v140
	v_rcp_f32_e32 v141, v141
	v_rcp_f32_e32 v142, v142
	v_rcp_f32_e32 v143, v143
	v_pk_mul_f32 v[140:141], v[132:133], v[140:141]
	v_pk_mul_f32 v[142:143], v[134:135], v[142:143]
; __device__ __forceinline__ unsigned pk2(float lo, float hi) { unsigned r; asm("v_cvt_pk_bf16_f32 %0, %1, %2" : "=v"(r) : "v"(lo), "v"(hi)); return r; }
; __device__ __forceinline__ float gelu_tanh(float x) { const float y = 1.5957691216f * (x + 0.044715f * x * x * x); return x * __builtin_amdgcn_rcpf(1.0f + __expf(-y)); }
;     __device__ __forceinline__ void operator()(const f32x4 (&acc)[2][2][4][2], const Unit& u, int wr, int wc, int fr, int fq) const {
;     ...
;         for (int n = 0; n < 2; ++n) {
;             asm volatile("" ::: "memory");
;             const int jc = j0 + 4 * n;
;             const f32x4 wg0 = *(const f32x4*)(wconv + jc), wg1 = *(const f32x4*)(wconv + 2 * DFF + jc), wg2 = *(const f32x4*)(wconv + 4 * DFF + jc), bg = *(const f32x4*)(bconv + jc);
;             const f32x4 wv0 = *(const f32x4*)(wconv + DFF + jc), wv1 = *(const f32x4*)(wconv + 3 * DFF + jc), wv2 = *(const f32x4*)(wconv + 5 * DFF + jc), bv = *(const f32x4*)(bconv + DFF + jc);
; #pragma unroll
;             for (int ai = 0; ai < 2; ++ai)
; #pragma unroll
;                 for (int m = 0; m < 4; ++m) { const int row = row0 + ai * HALF + m * 16;
;                     const f32x4 g0 = acc[ai][0][m][n], v0 = acc[ai][1][m][n];
;                     f32x4 gp = (f32x4){0.f, 0.f, 0.f, 0.f}, vp = gp;
;                     if (m > 0) { gp = acc[ai][0][m > 0 ? m - 1 : 0][n]; vp = acc[ai][1][m > 0 ? m - 1 : 0][n]; }
;                     f32x4 f;
; #pragma unroll
;                     for (int j = 0; j < 4; ++j) {
;                         const float g1 = dpp_shr1(dpp_ror1(gp[j]), g0[j]), g2 = dpp_shr2(dpp_ror2(gp[j]), g0[j]);
;                         const float v1 = dpp_shr1(dpp_ror1(vp[j]), v0[j]), v2 = dpp_shr2(dpp_ror2(vp[j]), v0[j]);
;                         const float cg_ = bg[j] + g2 * wg0[j] + g1 * wg1[j] + g0[j] * wg2[j];
;                         const float cv_ = bv[j] + v2 * wv0[j] + v1 * wv1[j] + v0[j] * wv2[j];
;                         f[j] = gelu_tanh(cg_) * cv_; }
;                     u32x2 w; w.x = pk2(f[0], f[1]); w.y = pk2(f[2], f[3]);
;                     if (n == 0) res0[ai * 4 + m] = w;
;                     else if (m > 0 || fr >= 2) { u32x4 w4; w4.x = res0[ai * 4 + m].x; w4.y = res0[ai * 4 + m].y; w4.z = w.x; w4.w = w.y; *(u32x4*)(F + (size_t)row * DFF + j0) = w4; }
	v_pk_mul_f32 v[140:141], v[140:141], v[136:137]
	v_pk_mul_f32 v[142:143], v[142:143], v[138:139]
	v_cvt_pk_bf16_f32 v252, v140, v141
	v_cvt_pk_bf16_f32 v253, v142, v143
	v_add_u32_e32 v144, 0x10, v248
	v_mad_u64_u32 v[144:145], vcc, v144, s4, v[242:243]
	global_store_dwordx4 v[144:145], v[250:253], off
	v_pk_fma_f32 v[132:133], v[100:101], v[158:159], v[146:147]
	v_pk_fma_f32 v[136:137], v[80:81], v[174:175], v[162:163]
	v_pk_fma_f32 v[134:135], v[102:103], v[160:161], v[148:149]
	v_pk_fma_f32 v[138:139], v[82:83], v[176:177], v[164:165]
	v_fmac_f32_dpp v132, v100, v154 row_shr:1 row_mask:0xf bank_mask:0xf
	v_fmac_f32_dpp v133, v101, v155 row_shr:1 row_mask:0xf bank_mask:0xf
	v_fmac_f32_dpp v134, v102, v156 row_shr:1 row_mask:0xf bank_mask:0xf
	v_fmac_f32_dpp v135, v103, v157 row_shr:1 row_mask:0xf bank_mask:0xf
	v_fmac_f32_dpp v136, v80, v170 row_shr:1 row_mask:0xf bank_mask:0xf
	v_fmac_f32_dpp v137, v81, v171 row_shr:1 row_mask:0xf bank_mask:0xf
	v_fmac_f32_dpp v138, v82, v172 row_shr:1 row_mask:0xf bank_mask:0xf
	v_fmac_f32_dpp v139, v83, v173 row_shr:1 row_mask:0xf bank_mask:0xf
	v_fmac_f32_dpp v132, v116, v154 row_shl:15 row_mask:0xf bank_mask:0xf
	v_fmac_f32_dpp v133, v117, v155 row_shl:15 row_mask:0xf bank_mask:0xf
	v_fmac_f32_dpp v134, v118, v156 row_shl:15 row_mask:0xf bank_mask:0xf
	v_fmac_f32_dpp v135, v119, v157 row_shl:15 row_mask:0xf bank_mask:0xf
	v_fmac_f32_dpp v136, v96, v170 row_shl:15 row_mask:0xf bank_mask:0xf
	v_fmac_f32_dpp v137, v97, v171 row_shl:15 row_mask:0xf bank_mask:0xf
	v_fmac_f32_dpp v138, v98, v172 row_shl:15 row_mask:0xf bank_mask:0xf
	v_fmac_f32_dpp v139, v99, v173 row_shl:15 row_mask:0xf bank_mask:0xf
	v_fmac_f32_dpp v132, v100, v150 row_shr:2 row_mask:0xf bank_mask:0xf
	v_fmac_f32_dpp v133, v101, v151 row_shr:2 row_mask:0xf bank_mask:0xf
	v_fmac_f32_dpp v134, v102, v152 row_shr:2 row_mask:0xf bank_mask:0xf
	v_fmac_f32_dpp v135, v103, v153 row_shr:2 row_mask:0xf bank_mask:0xf
	v_fmac_f32_dpp v136, v80, v166 row_shr:2 row_mask:0xf bank_mask:0xf
	v_fmac_f32_dpp v137, v81, v167 row_shr:2 row_mask:0xf bank_mask:0xf
	v_fmac_f32_dpp v138, v82, v168 row_shr:2 row_mask:0xf bank_mask:0xf
	v_fmac_f32_dpp v139, v83, v169 row_shr:2 row_mask:0xf bank_mask:0xf
	v_fmac_f32_dpp v132, v116, v150 row_shl:14 row_mask:0xf bank_mask:0xf
	v_fmac_f32_dpp v133, v117, v151 row_shl:14 row_mask:0xf bank_mask:0xf
	v_fmac_f32_dpp v134, v118, v152 row_shl:14 row_mask:0xf bank_mask:0xf
	v_fmac_f32_dpp v135, v119, v153 row_shl:14 row_mask:0xf bank_mask:0xf
	v_fmac_f32_dpp v136, v96, v166 row_shl:14 row_mask:0xf bank_mask:0xf
	v_fmac_f32_dpp v137, v97, v167 row_shl:14 row_mask:0xf bank_mask:0xf
	v_fmac_f32_dpp v138, v98, v168 row_shl:14 row_mask:0xf bank_mask:0xf
	v_fmac_f32_dpp v139, v99, v169 row_shl:14 row_mask:0xf bank_mask:0xf
	v_pk_mul_f32 v[140:141], v[132:133], v[132:133]
	v_pk_mul_f32 v[142:143], v[134:135], v[134:135]
	v_pk_fma_f32 v[140:141], v[140:141], s[98:99], v[244:245]
	v_pk_fma_f32 v[142:143], v[142:143], s[98:99], v[244:245]
	v_pk_mul_f32 v[140:141], v[132:133], v[140:141]
	v_pk_mul_f32 v[142:143], v[134:135], v[142:143]
	v_exp_f32_e32 v140, v140
	v_exp_f32_e32 v141, v141
	v_exp_f32_e32 v142, v142
	v_exp_f32_e32 v143, v143
	v_pk_add_f32 v[140:141], v[140:141], s[100:101]
	v_pk_add_f32 v[142:143], v[142:143], s[100:101]
	v_rcp_f32_e32 v140, v140
	v_rcp_f32_e32 v141, v141
	v_rcp_f32_e32 v142, v142
	v_rcp_f32_e32 v143, v143
	v_pk_mul_f32 v[140:141], v[132:133], v[140:141]
	v_pk_mul_f32 v[142:143], v[134:135], v[142:143]
	v_pk_mul_f32 v[140:141], v[140:141], v[136:137]
	v_pk_mul_f32 v[142:143], v[142:143], v[138:139]
	v_cvt_pk_bf16_f32 v128, v140, v141
	v_cvt_pk_bf16_f32 v129, v142, v143
	v_pk_fma_f32 v[132:133], v[92:93], v[190:191], v[178:179]
	v_pk_fma_f32 v[136:137], v[72:73], v[206:207], v[194:195]
	v_pk_fma_f32 v[134:135], v[94:95], v[192:193], v[180:181]
	v_pk_fma_f32 v[138:139], v[74:75], v[208:209], v[196:197]
	v_fmac_f32_dpp v132, v92, v186 row_shr:1 row_mask:0xf bank_mask:0xf
	v_fmac_f32_dpp v133, v93, v187 row_shr:1 row_mask:0xf bank_mask:0xf
	v_fmac_f32_dpp v134, v94, v188 row_shr:1 row_mask:0xf bank_mask:0xf
	v_fmac_f32_dpp v135, v95, v189 row_shr:1 row_mask:0xf bank_mask:0xf
	v_fmac_f32_dpp v136, v72, v202 row_shr:1 row_mask:0xf bank_mask:0xf
	v_fmac_f32_dpp v137, v73, v203 row_shr:1 row_mask:0xf bank_mask:0xf
	v_fmac_f32_dpp v138, v74, v204 row_shr:1 row_mask:0xf bank_mask:0xf
	v_fmac_f32_dpp v139, v75, v205 row_shr:1 row_mask:0xf bank_mask:0xf
	v_fmac_f32_dpp v132, v108, v186 row_shl:15 row_mask:0xf bank_mask:0xf
	v_fmac_f32_dpp v133, v109, v187 row_shl:15 row_mask:0xf bank_mask:0xf
	v_fmac_f32_dpp v134, v110, v188 row_shl:15 row_mask:0xf bank_mask:0xf
	v_fmac_f32_dpp v135, v111, v189 row_shl:15 row_mask:0xf bank_mask:0xf
	v_fmac_f32_dpp v136, v88, v202 row_shl:15 row_mask:0xf bank_mask:0xf
	v_fmac_f32_dpp v137, v89, v203 row_shl:15 row_mask:0xf bank_mask:0xf
	v_fmac_f32_dpp v138, v90, v204 row_shl:15 row_mask:0xf bank_mask:0xf
	v_fmac_f32_dpp v139, v91, v205 row_shl:15 row_mask:0xf bank_mask:0xf
	v_fmac_f32_dpp v132, v92, v182 row_shr:2 row_mask:0xf bank_mask:0xf
	v_fmac_f32_dpp v133, v93, v183 row_shr:2 row_mask:0xf bank_mask:0xf
	v_fmac_f32_dpp v134, v94, v184 row_shr:2 row_mask:0xf bank_mask:0xf
	v_fmac_f32_dpp v135, v95, v185 row_shr:2 row_mask:0xf bank_mask:0xf
	v_fmac_f32_dpp v136, v72, v198 row_shr:2 row_mask:0xf bank_mask:0xf
	v_fmac_f32_dpp v137, v73, v199 row_shr:2 row_mask:0xf bank_mask:0xf
	v_fmac_f32_dpp v138, v74, v200 row_shr:2 row_mask:0xf bank_mask:0xf
	v_fmac_f32_dpp v139, v75, v201 row_shr:2 row_mask:0xf bank_mask:0xf
	v_fmac_f32_dpp v132, v108, v182 row_shl:14 row_mask:0xf bank_mask:0xf
; __device__ __forceinline__ unsigned pk2(float lo, float hi) { unsigned r; asm("v_cvt_pk_bf16_f32 %0, %1, %2" : "=v"(r) : "v"(lo), "v"(hi)); return r; }
; __device__ __forceinline__ float gelu_tanh(float x) { const float y = 1.5957691216f * (x + 0.044715f * x * x * x); return x * __builtin_amdgcn_rcpf(1.0f + __expf(-y)); }
;     __device__ __forceinline__ void operator()(const f32x4 (&acc)[2][2][4][2], const Unit& u, int wr, int wc, int fr, int fq) const {
;     ...
;         for (int n = 0; n < 2; ++n) {
;             asm volatile("" ::: "memory");
;             const int jc = j0 + 4 * n;
;             const f32x4 wg0 = *(const f32x4*)(wconv + jc), wg1 = *(const f32x4*)(wconv + 2 * DFF + jc), wg2 = *(const f32x4*)(wconv + 4 * DFF + jc), bg = *(const f32x4*)(bconv + jc);
;             const f32x4 wv0 = *(const f32x4*)(wconv + DFF + jc), wv1 = *(const f32x4*)(wconv + 3 * DFF + jc), wv2 = *(const f32x4*)(wconv + 5 * DFF + jc), bv = *(const f32x4*)(bconv + DFF + jc);
; #pragma unroll
;             for (int ai = 0; ai < 2; ++ai)
; #pragma unroll
;                 for (int m = 0; m < 4; ++m) { const int row = row0 + ai * HALF + m * 16;
;                     const f32x4 g0 = acc[ai][0][m][n], v0 = acc[ai][1][m][n];
;                     f32x4 gp = (f32x4){0.f, 0.f, 0.f, 0.f}, vp = gp;
;                     if (m > 0) { gp = acc[ai][0][m > 0 ? m - 1 : 0][n]; vp = acc[ai][1][m > 0 ? m - 1 : 0][n]; }
;                     f32x4 f;
; #pragma unroll
;                     for (int j = 0; j < 4; ++j) {
;                         const float g1 = dpp_shr1(dpp_ror1(gp[j]), g0[j]), g2 = dpp_shr2(dpp_ror2(gp[j]), g0[j]);
;                         const float v1 = dpp_shr1(dpp_ror1(vp[j]), v0[j]), v2 = dpp_shr2(dpp_ror2(vp[j]), v0[j]);
;                         const float cg_ = bg[j] + g2 * wg0[j] + g1 * wg1[j] + g0[j] * wg2[j];
;                         const float cv_ = bv[j] + v2 * wv0[j] + v1 * wv1[j] + v0[j] * wv2[j];
;                         f[j] = gelu_tanh(cg_) * cv_; }
;                     u32x2 w; w.x = pk2(f[0], f[1]); w.y = pk2(f[2], f[3]);
;                     if (n == 0) res0[ai * 4 + m] = w;
;                     else if (m > 0 || fr >= 2) { u32x4 w4; w4.x = res0[ai * 4 + m].x; w4.y = res0[ai * 4 + m].y; w4.z = w.x; w4.w = w.y; *(u32x4*)(F + (size_t)row * DFF + j0) = w4; }
	v_fmac_f32_dpp v133, v109, v183 row_shl:14 row_mask:0xf bank_mask:0xf
	v_fmac_f32_dpp v134, v110, v184 row_shl:14 row_mask:0xf bank_mask:0xf
	v_fmac_f32_dpp v135, v111, v185 row_shl:14 row_mask:0xf bank_mask:0xf
	v_fmac_f32_dpp v136, v88, v198 row_shl:14 row_mask:0xf bank_mask:0xf
	v_fmac_f32_dpp v137, v89, v199 row_shl:14 row_mask:0xf bank_mask:0xf
	v_fmac_f32_dpp v138, v90, v200 row_shl:14 row_mask:0xf bank_mask:0xf
	v_fmac_f32_dpp v139, v91, v201 row_shl:14 row_mask:0xf bank_mask:0xf
	v_pk_mul_f32 v[140:141], v[132:133], v[132:133]
	v_pk_mul_f32 v[142:143], v[134:135], v[134:135]
	v_pk_fma_f32 v[140:141], v[140:141], s[98:99], v[244:245]
	v_pk_fma_f32 v[142:143], v[142:143], s[98:99], v[244:245]
	v_pk_mul_f32 v[140:141], v[132:133], v[140:141]
	v_pk_mul_f32 v[142:143], v[134:135], v[142:143]
	v_exp_f32_e32 v140, v140
	v_exp_f32_e32 v141, v141
	v_exp_f32_e32 v142, v142
	v_exp_f32_e32 v143, v143
	v_pk_add_f32 v[140:141], v[140:141], s[100:101]
	v_pk_add_f32 v[142:143], v[142:143], s[100:101]
	v_rcp_f32_e32 v140, v140
	v_rcp_f32_e32 v141, v141
	v_rcp_f32_e32 v142, v142
	v_rcp_f32_e32 v143, v143
	v_pk_mul_f32 v[140:141], v[132:133], v[140:141]
	v_pk_mul_f32 v[142:143], v[134:135], v[142:143]
	v_pk_mul_f32 v[140:141], v[140:141], v[136:137]
	v_pk_mul_f32 v[142:143], v[142:143], v[138:139]
	v_cvt_pk_bf16_f32 v130, v140, v141
	v_cvt_pk_bf16_f32 v131, v142, v143
	v_add_u32_e32 v144, 0x20, v248
	v_mad_u64_u32 v[144:145], vcc, v144, s4, v[242:243]
	global_store_dwordx4 v[144:145], v[128:131], off
	v_pk_fma_f32 v[132:133], v[84:85], v[158:159], v[146:147]
	v_pk_fma_f32 v[136:137], v[68:69], v[174:175], v[162:163]
	v_pk_fma_f32 v[134:135], v[86:87], v[160:161], v[148:149]
	v_pk_fma_f32 v[138:139], v[70:71], v[176:177], v[164:165]
	v_fmac_f32_dpp v132, v84, v154 row_shr:1 row_mask:0xf bank_mask:0xf
	v_fmac_f32_dpp v133, v85, v155 row_shr:1 row_mask:0xf bank_mask:0xf
	v_fmac_f32_dpp v134, v86, v156 row_shr:1 row_mask:0xf bank_mask:0xf
	v_fmac_f32_dpp v135, v87, v157 row_shr:1 row_mask:0xf bank_mask:0xf
	v_fmac_f32_dpp v136, v68, v170 row_shr:1 row_mask:0xf bank_mask:0xf
	v_fmac_f32_dpp v137, v69, v171 row_shr:1 row_mask:0xf bank_mask:0xf
	v_fmac_f32_dpp v138, v70, v172 row_shr:1 row_mask:0xf bank_mask:0xf
	v_fmac_f32_dpp v139, v71, v173 row_shr:1 row_mask:0xf bank_mask:0xf
	v_fmac_f32_dpp v132, v100, v154 row_shl:15 row_mask:0xf bank_mask:0xf
	v_fmac_f32_dpp v133, v101, v155 row_shl:15 row_mask:0xf bank_mask:0xf
	v_fmac_f32_dpp v134, v102, v156 row_shl:15 row_mask:0xf bank_mask:0xf
	v_fmac_f32_dpp v135, v103, v157 row_shl:15 row_mask:0xf bank_mask:0xf
	v_fmac_f32_dpp v136, v80, v170 row_shl:15 row_mask:0xf bank_mask:0xf
	v_fmac_f32_dpp v137, v81, v171 row_shl:15 row_mask:0xf bank_mask:0xf
	v_fmac_f32_dpp v138, v82, v172 row_shl:15 row_mask:0xf bank_mask:0xf
	v_fmac_f32_dpp v139, v83, v173 row_shl:15 row_mask:0xf bank_mask:0xf
	v_fmac_f32_dpp v132, v84, v150 row_shr:2 row_mask:0xf bank_mask:0xf
	v_fmac_f32_dpp v133, v85, v151 row_shr:2 row_mask:0xf bank_mask:0xf
	v_fmac_f32_dpp v134, v86, v152 row_shr:2 row_mask:0xf bank_mask:0xf
	v_fmac_f32_dpp v135, v87, v153 row_shr:2 row_mask:0xf bank_mask:0xf
	v_fmac_f32_dpp v136, v68, v166 row_shr:2 row_mask:0xf bank_mask:0xf
	v_fmac_f32_dpp v137, v69, v167 row_shr:2 row_mask:0xf bank_mask:0xf
	v_fmac_f32_dpp v138, v70, v168 row_shr:2 row_mask:0xf bank_mask:0xf
	v_fmac_f32_dpp v139, v71, v169 row_shr:2 row_mask:0xf bank_mask:0xf
	v_fmac_f32_dpp v132, v100, v150 row_shl:14 row_mask:0xf bank_mask:0xf
	v_fmac_f32_dpp v133, v101, v151 row_shl:14 row_mask:0xf bank_mask:0xf
	v_fmac_f32_dpp v134, v102, v152 row_shl:14 row_mask:0xf bank_mask:0xf
	v_fmac_f32_dpp v135, v103, v153 row_shl:14 row_mask:0xf bank_mask:0xf
	v_fmac_f32_dpp v136, v80, v166 row_shl:14 row_mask:0xf bank_mask:0xf
	v_fmac_f32_dpp v137, v81, v167 row_shl:14 row_mask:0xf bank_mask:0xf
	v_fmac_f32_dpp v138, v82, v168 row_shl:14 row_mask:0xf bank_mask:0xf
	v_fmac_f32_dpp v139, v83, v169 row_shl:14 row_mask:0xf bank_mask:0xf
	v_pk_mul_f32 v[140:141], v[132:133], v[132:133]
	v_pk_mul_f32 v[142:143], v[134:135], v[134:135]
	v_pk_fma_f32 v[140:141], v[140:141], s[98:99], v[244:245]
	v_pk_fma_f32 v[142:143], v[142:143], s[98:99], v[244:245]
	v_pk_mul_f32 v[140:141], v[132:133], v[140:141]
	v_pk_mul_f32 v[142:143], v[134:135], v[142:143]
	v_exp_f32_e32 v140, v140
	v_exp_f32_e32 v141, v141
	v_exp_f32_e32 v142, v142
	v_exp_f32_e32 v143, v143
	v_pk_add_f32 v[140:141], v[140:141], s[100:101]
	v_pk_add_f32 v[142:143], v[142:143], s[100:101]
	v_rcp_f32_e32 v140, v140
	v_rcp_f32_e32 v141, v141
	v_rcp_f32_e32 v142, v142
	v_rcp_f32_e32 v143, v143
	v_pk_mul_f32 v[140:141], v[132:133], v[140:141]
	v_pk_mul_f32 v[142:143], v[134:135], v[142:143]
	v_pk_mul_f32 v[140:141], v[140:141], v[136:137]
	v_pk_mul_f32 v[142:143], v[142:143], v[138:139]
	v_cvt_pk_bf16_f32 v250, v140, v141
	v_cvt_pk_bf16_f32 v251, v142, v143
	v_pk_fma_f32 v[132:133], v[76:77], v[190:191], v[178:179]
	v_pk_fma_f32 v[136:137], v[64:65], v[206:207], v[194:195]
	v_pk_fma_f32 v[134:135], v[78:79], v[192:193], v[180:181]
	v_pk_fma_f32 v[138:139], v[66:67], v[208:209], v[196:197]
	v_fmac_f32_dpp v132, v76, v186 row_shr:1 row_mask:0xf bank_mask:0xf
	v_fmac_f32_dpp v133, v77, v187 row_shr:1 row_mask:0xf bank_mask:0xf
	v_fmac_f32_dpp v134, v78, v188 row_shr:1 row_mask:0xf bank_mask:0xf
	v_fmac_f32_dpp v135, v79, v189 row_shr:1 row_mask:0xf bank_mask:0xf
	v_fmac_f32_dpp v136, v64, v202 row_shr:1 row_mask:0xf bank_mask:0xf
	v_fmac_f32_dpp v137, v65, v203 row_shr:1 row_mask:0xf bank_mask:0xf
	v_fmac_f32_dpp v138, v66, v204 row_shr:1 row_mask:0xf bank_mask:0xf
	v_fmac_f32_dpp v139, v67, v205 row_shr:1 row_mask:0xf bank_mask:0xf
; __device__ __forceinline__ unsigned pk2(float lo, float hi) { unsigned r; asm("v_cvt_pk_bf16_f32 %0, %1, %2" : "=v"(r) : "v"(lo), "v"(hi)); return r; }
; __device__ __forceinline__ float gelu_tanh(float x) { const float y = 1.5957691216f * (x + 0.044715f * x * x * x); return x * __builtin_amdgcn_rcpf(1.0f + __expf(-y)); }
;     __device__ __forceinline__ void operator()(const f32x4 (&acc)[2][2][4][2], const Unit& u, int wr, int wc, int fr, int fq) const {
;     ...
;         for (int n = 0; n < 2; ++n) {
;             asm volatile("" ::: "memory");
;             const int jc = j0 + 4 * n;
;             const f32x4 wg0 = *(const f32x4*)(wconv + jc), wg1 = *(const f32x4*)(wconv + 2 * DFF + jc), wg2 = *(const f32x4*)(wconv + 4 * DFF + jc), bg = *(const f32x4*)(bconv + jc);
;             const f32x4 wv0 = *(const f32x4*)(wconv + DFF + jc), wv1 = *(const f32x4*)(wconv + 3 * DFF + jc), wv2 = *(const f32x4*)(wconv + 5 * DFF + jc), bv = *(const f32x4*)(bconv + DFF + jc);
; #pragma unroll
;             for (int ai = 0; ai < 2; ++ai)
; #pragma unroll
;                 for (int m = 0; m < 4; ++m) { const int row = row0 + ai * HALF + m * 16;
;                     const f32x4 g0 = acc[ai][0][m][n], v0 = acc[ai][1][m][n];
;                     f32x4 gp = (f32x4){0.f, 0.f, 0.f, 0.f}, vp = gp;
;                     if (m > 0) { gp = acc[ai][0][m > 0 ? m - 1 : 0][n]; vp = acc[ai][1][m > 0 ? m - 1 : 0][n]; }
;                     f32x4 f;
; #pragma unroll
;                     for (int j = 0; j < 4; ++j) {
;                         const float g1 = dpp_shr1(dpp_ror1(gp[j]), g0[j]), g2 = dpp_shr2(dpp_ror2(gp[j]), g0[j]);
;                         const float v1 = dpp_shr1(dpp_ror1(vp[j]), v0[j]), v2 = dpp_shr2(dpp_ror2(vp[j]), v0[j]);
;                         const float cg_ = bg[j] + g2 * wg0[j] + g1 * wg1[j] + g0[j] * wg2[j];
;                         const float cv_ = bv[j] + v2 * wv0[j] + v1 * wv1[j] + v0[j] * wv2[j];
;                         f[j] = gelu_tanh(cg_) * cv_; }
;                     u32x2 w; w.x = pk2(f[0], f[1]); w.y = pk2(f[2], f[3]);
;                     if (n == 0) res0[ai * 4 + m] = w;
;                     else if (m > 0 || fr >= 2) { u32x4 w4; w4.x = res0[ai * 4 + m].x; w4.y = res0[ai * 4 + m].y; w4.z = w.x; w4.w = w.y; *(u32x4*)(F + (size_t)row * DFF + j0) = w4; }
	v_fmac_f32_dpp v132, v92, v186 row_shl:15 row_mask:0xf bank_mask:0xf
	v_fmac_f32_dpp v133, v93, v187 row_shl:15 row_mask:0xf bank_mask:0xf
	v_fmac_f32_dpp v134, v94, v188 row_shl:15 row_mask:0xf bank_mask:0xf
	v_fmac_f32_dpp v135, v95, v189 row_shl:15 row_mask:0xf bank_mask:0xf
	v_fmac_f32_dpp v136, v72, v202 row_shl:15 row_mask:0xf bank_mask:0xf
	v_fmac_f32_dpp v137, v73, v203 row_shl:15 row_mask:0xf bank_mask:0xf
	v_fmac_f32_dpp v138, v74, v204 row_shl:15 row_mask:0xf bank_mask:0xf
	v_fmac_f32_dpp v139, v75, v205 row_shl:15 row_mask:0xf bank_mask:0xf
	v_fmac_f32_dpp v132, v76, v182 row_shr:2 row_mask:0xf bank_mask:0xf
	v_fmac_f32_dpp v133, v77, v183 row_shr:2 row_mask:0xf bank_mask:0xf
	v_fmac_f32_dpp v134, v78, v184 row_shr:2 row_mask:0xf bank_mask:0xf
	v_fmac_f32_dpp v135, v79, v185 row_shr:2 row_mask:0xf bank_mask:0xf
	v_fmac_f32_dpp v136, v64, v198 row_shr:2 row_mask:0xf bank_mask:0xf
	v_fmac_f32_dpp v137, v65, v199 row_shr:2 row_mask:0xf bank_mask:0xf
	v_fmac_f32_dpp v138, v66, v200 row_shr:2 row_mask:0xf bank_mask:0xf
	v_fmac_f32_dpp v139, v67, v201 row_shr:2 row_mask:0xf bank_mask:0xf
	v_fmac_f32_dpp v132, v92, v182 row_shl:14 row_mask:0xf bank_mask:0xf
	v_fmac_f32_dpp v133, v93, v183 row_shl:14 row_mask:0xf bank_mask:0xf
	v_fmac_f32_dpp v134, v94, v184 row_shl:14 row_mask:0xf bank_mask:0xf
	v_fmac_f32_dpp v135, v95, v185 row_shl:14 row_mask:0xf bank_mask:0xf
	v_fmac_f32_dpp v136, v72, v198 row_shl:14 row_mask:0xf bank_mask:0xf
	v_fmac_f32_dpp v137, v73, v199 row_shl:14 row_mask:0xf bank_mask:0xf
	v_fmac_f32_dpp v138, v74, v200 row_shl:14 row_mask:0xf bank_mask:0xf
	v_fmac_f32_dpp v139, v75, v201 row_shl:14 row_mask:0xf bank_mask:0xf
	v_pk_mul_f32 v[140:141], v[132:133], v[132:133]
	v_pk_mul_f32 v[142:143], v[134:135], v[134:135]
	v_pk_fma_f32 v[140:141], v[140:141], s[98:99], v[244:245]
	v_pk_fma_f32 v[142:143], v[142:143], s[98:99], v[244:245]
	v_pk_mul_f32 v[140:141], v[132:133], v[140:141]
	v_pk_mul_f32 v[142:143], v[134:135], v[142:143]
	v_exp_f32_e32 v140, v140
	v_exp_f32_e32 v141, v141
	v_exp_f32_e32 v142, v142
	v_exp_f32_e32 v143, v143
	v_pk_add_f32 v[140:141], v[140:141], s[100:101]
	v_pk_add_f32 v[142:143], v[142:143], s[100:101]
	v_rcp_f32_e32 v140, v140
	v_rcp_f32_e32 v141, v141
	v_rcp_f32_e32 v142, v142
	v_rcp_f32_e32 v143, v143
	v_pk_mul_f32 v[140:141], v[132:133], v[140:141]
	v_pk_mul_f32 v[142:143], v[134:135], v[142:143]
	v_pk_mul_f32 v[140:141], v[140:141], v[136:137]
	v_pk_mul_f32 v[142:143], v[142:143], v[138:139]
	v_cvt_pk_bf16_f32 v252, v140, v141
	v_cvt_pk_bf16_f32 v253, v142, v143
	v_add_u32_e32 v144, 0x30, v248
	v_mad_u64_u32 v[144:145], vcc, v144, s4, v[242:243]
	global_store_dwordx4 v[144:145], v[250:253], off
	v_pk_fma_f32 v[132:133], v[60:61], v[158:159], v[146:147]
	v_pk_fma_f32 v[136:137], v[48:49], v[174:175], v[162:163]
	v_pk_fma_f32 v[134:135], v[62:63], v[160:161], v[148:149]
	v_pk_fma_f32 v[138:139], v[50:51], v[176:177], v[164:165]
	v_fmac_f32_dpp v132, v60, v154 row_shr:1 row_mask:0xf bank_mask:0xf
	v_fmac_f32_dpp v133, v61, v155 row_shr:1 row_mask:0xf bank_mask:0xf
	v_fmac_f32_dpp v134, v62, v156 row_shr:1 row_mask:0xf bank_mask:0xf
	v_fmac_f32_dpp v135, v63, v157 row_shr:1 row_mask:0xf bank_mask:0xf
	v_fmac_f32_dpp v136, v48, v170 row_shr:1 row_mask:0xf bank_mask:0xf
	v_fmac_f32_dpp v137, v49, v171 row_shr:1 row_mask:0xf bank_mask:0xf
	v_fmac_f32_dpp v138, v50, v172 row_shr:1 row_mask:0xf bank_mask:0xf
	v_fmac_f32_dpp v139, v51, v173 row_shr:1 row_mask:0xf bank_mask:0xf
	v_fmac_f32_dpp v132, v60, v150 row_shr:2 row_mask:0xf bank_mask:0xf
	v_fmac_f32_dpp v133, v61, v151 row_shr:2 row_mask:0xf bank_mask:0xf
	v_fmac_f32_dpp v134, v62, v152 row_shr:2 row_mask:0xf bank_mask:0xf
	v_fmac_f32_dpp v135, v63, v153 row_shr:2 row_mask:0xf bank_mask:0xf
	v_fmac_f32_dpp v136, v48, v166 row_shr:2 row_mask:0xf bank_mask:0xf
	v_fmac_f32_dpp v137, v49, v167 row_shr:2 row_mask:0xf bank_mask:0xf
	v_fmac_f32_dpp v138, v50, v168 row_shr:2 row_mask:0xf bank_mask:0xf
	v_fmac_f32_dpp v139, v51, v169 row_shr:2 row_mask:0xf bank_mask:0xf
	v_pk_mul_f32 v[140:141], v[132:133], v[132:133]
	v_pk_mul_f32 v[142:143], v[134:135], v[134:135]
	v_pk_fma_f32 v[140:141], v[140:141], s[98:99], v[244:245]
	v_pk_fma_f32 v[142:143], v[142:143], s[98:99], v[244:245]
	v_pk_mul_f32 v[140:141], v[132:133], v[140:141]
	v_pk_mul_f32 v[142:143], v[134:135], v[142:143]
	v_exp_f32_e32 v140, v140
	v_exp_f32_e32 v141, v141
	v_exp_f32_e32 v142, v142
	v_exp_f32_e32 v143, v143
	v_pk_add_f32 v[140:141], v[140:141], s[100:101]
	v_pk_add_f32 v[142:143], v[142:143], s[100:101]
	v_rcp_f32_e32 v140, v140
	v_rcp_f32_e32 v141, v141
	v_rcp_f32_e32 v142, v142
	v_rcp_f32_e32 v143, v143
	v_pk_mul_f32 v[140:141], v[132:133], v[140:141]
	v_pk_mul_f32 v[142:143], v[134:135], v[142:143]
	v_pk_mul_f32 v[140:141], v[140:141], v[136:137]
	v_pk_mul_f32 v[142:143], v[142:143], v[138:139]
	v_cvt_pk_bf16_f32 v128, v140, v141
	v_cvt_pk_bf16_f32 v129, v142, v143
	v_pk_fma_f32 v[132:133], v[56:57], v[190:191], v[178:179]
	v_pk_fma_f32 v[136:137], v[40:41], v[206:207], v[194:195]
	v_pk_fma_f32 v[134:135], v[58:59], v[192:193], v[180:181]
	v_pk_fma_f32 v[138:139], v[42:43], v[208:209], v[196:197]
	v_fmac_f32_dpp v132, v56, v186 row_shr:1 row_mask:0xf bank_mask:0xf
	v_fmac_f32_dpp v133, v57, v187 row_shr:1 row_mask:0xf bank_mask:0xf
	v_fmac_f32_dpp v134, v58, v188 row_shr:1 row_mask:0xf bank_mask:0xf
	v_fmac_f32_dpp v135, v59, v189 row_shr:1 row_mask:0xf bank_mask:0xf
	v_fmac_f32_dpp v136, v40, v202 row_shr:1 row_mask:0xf bank_mask:0xf
	v_fmac_f32_dpp v137, v41, v203 row_shr:1 row_mask:0xf bank_mask:0xf
	v_fmac_f32_dpp v138, v42, v204 row_shr:1 row_mask:0xf bank_mask:0xf
; __device__ __forceinline__ unsigned pk2(float lo, float hi) { unsigned r; asm("v_cvt_pk_bf16_f32 %0, %1, %2" : "=v"(r) : "v"(lo), "v"(hi)); return r; }
; __device__ __forceinline__ float gelu_tanh(float x) { const float y = 1.5957691216f * (x + 0.044715f * x * x * x); return x * __builtin_amdgcn_rcpf(1.0f + __expf(-y)); }
;     __device__ __forceinline__ void operator()(const f32x4 (&acc)[2][2][4][2], const Unit& u, int wr, int wc, int fr, int fq) const {
;     ...
;         for (int n = 0; n < 2; ++n) {
;             asm volatile("" ::: "memory");
;             const int jc = j0 + 4 * n;
;             const f32x4 wg0 = *(const f32x4*)(wconv + jc), wg1 = *(const f32x4*)(wconv + 2 * DFF + jc), wg2 = *(const f32x4*)(wconv + 4 * DFF + jc), bg = *(const f32x4*)(bconv + jc);
;             const f32x4 wv0 = *(const f32x4*)(wconv + DFF + jc), wv1 = *(const f32x4*)(wconv + 3 * DFF + jc), wv2 = *(const f32x4*)(wconv + 5 * DFF + jc), bv = *(const f32x4*)(bconv + DFF + jc);
; #pragma unroll
;             for (int ai = 0; ai < 2; ++ai)
; #pragma unroll
;                 for (int m = 0; m < 4; ++m) { const int row = row0 + ai * HALF + m * 16;
;                     const f32x4 g0 = acc[ai][0][m][n], v0 = acc[ai][1][m][n];
;                     f32x4 gp = (f32x4){0.f, 0.f, 0.f, 0.f}, vp = gp;
;                     if (m > 0) { gp = acc[ai][0][m > 0 ? m - 1 : 0][n]; vp = acc[ai][1][m > 0 ? m - 1 : 0][n]; }
;                     f32x4 f;
; #pragma unroll
;                     for (int j = 0; j < 4; ++j) {
;                         const float g1 = dpp_shr1(dpp_ror1(gp[j]), g0[j]), g2 = dpp_shr2(dpp_ror2(gp[j]), g0[j]);
;                         const float v1 = dpp_shr1(dpp_ror1(vp[j]), v0[j]), v2 = dpp_shr2(dpp_ror2(vp[j]), v0[j]);
;                         const float cg_ = bg[j] + g2 * wg0[j] + g1 * wg1[j] + g0[j] * wg2[j];
;                         const float cv_ = bv[j] + v2 * wv0[j] + v1 * wv1[j] + v0[j] * wv2[j];
;                         f[j] = gelu_tanh(cg_) * cv_; }
;                     u32x2 w; w.x = pk2(f[0], f[1]); w.y = pk2(f[2], f[3]);
;                     if (n == 0) res0[ai * 4 + m] = w;
;                     else if (m > 0 || fr >= 2) { u32x4 w4; w4.x = res0[ai * 4 + m].x; w4.y = res0[ai * 4 + m].y; w4.z = w.x; w4.w = w.y; *(u32x4*)(F + (size_t)row * DFF + j0) = w4; }
	v_fmac_f32_dpp v139, v43, v205 row_shr:1 row_mask:0xf bank_mask:0xf
	v_fmac_f32_dpp v132, v56, v182 row_shr:2 row_mask:0xf bank_mask:0xf
	v_fmac_f32_dpp v133, v57, v183 row_shr:2 row_mask:0xf bank_mask:0xf
	v_fmac_f32_dpp v134, v58, v184 row_shr:2 row_mask:0xf bank_mask:0xf
	v_fmac_f32_dpp v135, v59, v185 row_shr:2 row_mask:0xf bank_mask:0xf
	v_fmac_f32_dpp v136, v40, v198 row_shr:2 row_mask:0xf bank_mask:0xf
	v_fmac_f32_dpp v137, v41, v199 row_shr:2 row_mask:0xf bank_mask:0xf
	v_fmac_f32_dpp v138, v42, v200 row_shr:2 row_mask:0xf bank_mask:0xf
	v_fmac_f32_dpp v139, v43, v201 row_shr:2 row_mask:0xf bank_mask:0xf
	v_pk_mul_f32 v[140:141], v[132:133], v[132:133]
	v_pk_mul_f32 v[142:143], v[134:135], v[134:135]
	v_pk_fma_f32 v[140:141], v[140:141], s[98:99], v[244:245]
	v_pk_fma_f32 v[142:143], v[142:143], s[98:99], v[244:245]
	v_pk_mul_f32 v[140:141], v[132:133], v[140:141]
	v_pk_mul_f32 v[142:143], v[134:135], v[142:143]
	v_exp_f32_e32 v140, v140
	v_exp_f32_e32 v141, v141
	v_exp_f32_e32 v142, v142
	v_exp_f32_e32 v143, v143
	v_pk_add_f32 v[140:141], v[140:141], s[100:101]
	v_pk_add_f32 v[142:143], v[142:143], s[100:101]
	v_rcp_f32_e32 v140, v140
	v_rcp_f32_e32 v141, v141
	v_rcp_f32_e32 v142, v142
	v_rcp_f32_e32 v143, v143
	v_pk_mul_f32 v[140:141], v[132:133], v[140:141]
	v_pk_mul_f32 v[142:143], v[134:135], v[142:143]
	v_pk_mul_f32 v[140:141], v[140:141], v[136:137]
	v_pk_mul_f32 v[142:143], v[142:143], v[138:139]
	v_cvt_pk_bf16_f32 v130, v140, v141
	v_cvt_pk_bf16_f32 v131, v142, v143
	s_and_saveexec_b64 s[42:43], s[8:9]
	v_add_u32_e32 v144, 0x80, v248
	v_mad_u64_u32 v[144:145], vcc, v144, s4, v[242:243]
	global_store_dwordx4 v[144:145], v[128:131], off
	s_or_b64 exec, exec, s[42:43]
	s_nop 4
	v_pk_fma_f32 v[132:133], v[52:53], v[158:159], v[146:147]
	v_pk_fma_f32 v[136:137], v[32:33], v[174:175], v[162:163]
	v_pk_fma_f32 v[134:135], v[54:55], v[160:161], v[148:149]
	v_pk_fma_f32 v[138:139], v[34:35], v[176:177], v[164:165]
	v_fmac_f32_dpp v132, v52, v154 row_shr:1 row_mask:0xf bank_mask:0xf
	v_fmac_f32_dpp v133, v53, v155 row_shr:1 row_mask:0xf bank_mask:0xf
	v_fmac_f32_dpp v134, v54, v156 row_shr:1 row_mask:0xf bank_mask:0xf
	v_fmac_f32_dpp v135, v55, v157 row_shr:1 row_mask:0xf bank_mask:0xf
	v_fmac_f32_dpp v136, v32, v170 row_shr:1 row_mask:0xf bank_mask:0xf
	v_fmac_f32_dpp v137, v33, v171 row_shr:1 row_mask:0xf bank_mask:0xf
	v_fmac_f32_dpp v138, v34, v172 row_shr:1 row_mask:0xf bank_mask:0xf
	v_fmac_f32_dpp v139, v35, v173 row_shr:1 row_mask:0xf bank_mask:0xf
	v_fmac_f32_dpp v132, v60, v154 row_shl:15 row_mask:0xf bank_mask:0xf
	v_fmac_f32_dpp v133, v61, v155 row_shl:15 row_mask:0xf bank_mask:0xf
	v_fmac_f32_dpp v134, v62, v156 row_shl:15 row_mask:0xf bank_mask:0xf
	v_fmac_f32_dpp v135, v63, v157 row_shl:15 row_mask:0xf bank_mask:0xf
	v_fmac_f32_dpp v136, v48, v170 row_shl:15 row_mask:0xf bank_mask:0xf
	v_fmac_f32_dpp v137, v49, v171 row_shl:15 row_mask:0xf bank_mask:0xf
	v_fmac_f32_dpp v138, v50, v172 row_shl:15 row_mask:0xf bank_mask:0xf
	v_fmac_f32_dpp v139, v51, v173 row_shl:15 row_mask:0xf bank_mask:0xf
	v_fmac_f32_dpp v132, v52, v150 row_shr:2 row_mask:0xf bank_mask:0xf
	v_fmac_f32_dpp v133, v53, v151 row_shr:2 row_mask:0xf bank_mask:0xf
	v_fmac_f32_dpp v134, v54, v152 row_shr:2 row_mask:0xf bank_mask:0xf
	v_fmac_f32_dpp v135, v55, v153 row_shr:2 row_mask:0xf bank_mask:0xf
	v_fmac_f32_dpp v136, v32, v166 row_shr:2 row_mask:0xf bank_mask:0xf
	v_fmac_f32_dpp v137, v33, v167 row_shr:2 row_mask:0xf bank_mask:0xf
	v_fmac_f32_dpp v138, v34, v168 row_shr:2 row_mask:0xf bank_mask:0xf
	v_fmac_f32_dpp v139, v35, v169 row_shr:2 row_mask:0xf bank_mask:0xf
	v_fmac_f32_dpp v132, v60, v150 row_shl:14 row_mask:0xf bank_mask:0xf
	v_fmac_f32_dpp v133, v61, v151 row_shl:14 row_mask:0xf bank_mask:0xf
	v_fmac_f32_dpp v134, v62, v152 row_shl:14 row_mask:0xf bank_mask:0xf
	v_fmac_f32_dpp v135, v63, v153 row_shl:14 row_mask:0xf bank_mask:0xf
	v_fmac_f32_dpp v136, v48, v166 row_shl:14 row_mask:0xf bank_mask:0xf
	v_fmac_f32_dpp v137, v49, v167 row_shl:14 row_mask:0xf bank_mask:0xf
	v_fmac_f32_dpp v138, v50, v168 row_shl:14 row_mask:0xf bank_mask:0xf
	v_fmac_f32_dpp v139, v51, v169 row_shl:14 row_mask:0xf bank_mask:0xf
	v_pk_mul_f32 v[140:141], v[132:133], v[132:133]
	v_pk_mul_f32 v[142:143], v[134:135], v[134:135]
	v_pk_fma_f32 v[140:141], v[140:141], s[98:99], v[244:245]
	v_pk_fma_f32 v[142:143], v[142:143], s[98:99], v[244:245]
	v_pk_mul_f32 v[140:141], v[132:133], v[140:141]
	v_pk_mul_f32 v[142:143], v[134:135], v[142:143]
	v_exp_f32_e32 v140, v140
	v_exp_f32_e32 v141, v141
	v_exp_f32_e32 v142, v142
	v_exp_f32_e32 v143, v143
	v_pk_add_f32 v[140:141], v[140:141], s[100:101]
	v_pk_add_f32 v[142:143], v[142:143], s[100:101]
	v_rcp_f32_e32 v140, v140
	v_rcp_f32_e32 v141, v141
	v_rcp_f32_e32 v142, v142
	v_rcp_f32_e32 v143, v143
	v_pk_mul_f32 v[140:141], v[132:133], v[140:141]
	v_pk_mul_f32 v[142:143], v[134:135], v[142:143]
	v_pk_mul_f32 v[140:141], v[140:141], v[136:137]
	v_pk_mul_f32 v[142:143], v[142:143], v[138:139]
	v_cvt_pk_bf16_f32 v250, v140, v141
	v_cvt_pk_bf16_f32 v251, v142, v143
	v_pk_fma_f32 v[132:133], v[44:45], v[190:191], v[178:179]
	v_pk_fma_f32 v[136:137], v[24:25], v[206:207], v[194:195]
	v_pk_fma_f32 v[134:135], v[46:47], v[192:193], v[180:181]
	v_pk_fma_f32 v[138:139], v[26:27], v[208:209], v[196:197]
	v_fmac_f32_dpp v132, v44, v186 row_shr:1 row_mask:0xf bank_mask:0xf
	v_fmac_f32_dpp v133, v45, v187 row_shr:1 row_mask:0xf bank_mask:0xf
	v_fmac_f32_dpp v134, v46, v188 row_shr:1 row_mask:0xf bank_mask:0xf
	v_fmac_f32_dpp v135, v47, v189 row_shr:1 row_mask:0xf bank_mask:0xf
	v_fmac_f32_dpp v136, v24, v202 row_shr:1 row_mask:0xf bank_mask:0xf
; __device__ __forceinline__ unsigned pk2(float lo, float hi) { unsigned r; asm("v_cvt_pk_bf16_f32 %0, %1, %2" : "=v"(r) : "v"(lo), "v"(hi)); return r; }
; __device__ __forceinline__ float gelu_tanh(float x) { const float y = 1.5957691216f * (x + 0.044715f * x * x * x); return x * __builtin_amdgcn_rcpf(1.0f + __expf(-y)); }
;     __device__ __forceinline__ void operator()(const f32x4 (&acc)[2][2][4][2], const Unit& u, int wr, int wc, int fr, int fq) const {
;     ...
;         for (int n = 0; n < 2; ++n) {
;             asm volatile("" ::: "memory");
;             const int jc = j0 + 4 * n;
;             const f32x4 wg0 = *(const f32x4*)(wconv + jc), wg1 = *(const f32x4*)(wconv + 2 * DFF + jc), wg2 = *(const f32x4*)(wconv + 4 * DFF + jc), bg = *(const f32x4*)(bconv + jc);
;             const f32x4 wv0 = *(const f32x4*)(wconv + DFF + jc), wv1 = *(const f32x4*)(wconv + 3 * DFF + jc), wv2 = *(const f32x4*)(wconv + 5 * DFF + jc), bv = *(const f32x4*)(bconv + DFF + jc);
; #pragma unroll
;             for (int ai = 0; ai < 2; ++ai)
; #pragma unroll
;                 for (int m = 0; m < 4; ++m) { const int row = row0 + ai * HALF + m * 16;
;                     const f32x4 g0 = acc[ai][0][m][n], v0 = acc[ai][1][m][n];
;                     f32x4 gp = (f32x4){0.f, 0.f, 0.f, 0.f}, vp = gp;
;                     if (m > 0) { gp = acc[ai][0][m > 0 ? m - 1 : 0][n]; vp = acc[ai][1][m > 0 ? m - 1 : 0][n]; }
;                     f32x4 f;
; #pragma unroll
;                     for (int j = 0; j < 4; ++j) {
;                         const float g1 = dpp_shr1(dpp_ror1(gp[j]), g0[j]), g2 = dpp_shr2(dpp_ror2(gp[j]), g0[j]);
;                         const float v1 = dpp_shr1(dpp_ror1(vp[j]), v0[j]), v2 = dpp_shr2(dpp_ror2(vp[j]), v0[j]);
;                         const float cg_ = bg[j] + g2 * wg0[j] + g1 * wg1[j] + g0[j] * wg2[j];
;                         const float cv_ = bv[j] + v2 * wv0[j] + v1 * wv1[j] + v0[j] * wv2[j];
;                         f[j] = gelu_tanh(cg_) * cv_; }
;                     u32x2 w; w.x = pk2(f[0], f[1]); w.y = pk2(f[2], f[3]);
;                     if (n == 0) res0[ai * 4 + m] = w;
;                     else if (m > 0 || fr >= 2) { u32x4 w4; w4.x = res0[ai * 4 + m].x; w4.y = res0[ai * 4 + m].y; w4.z = w.x; w4.w = w.y; *(u32x4*)(F + (size_t)row * DFF + j0) = w4; }
	v_fmac_f32_dpp v137, v25, v203 row_shr:1 row_mask:0xf bank_mask:0xf
	v_fmac_f32_dpp v138, v26, v204 row_shr:1 row_mask:0xf bank_mask:0xf
	v_fmac_f32_dpp v139, v27, v205 row_shr:1 row_mask:0xf bank_mask:0xf
	v_fmac_f32_dpp v132, v56, v186 row_shl:15 row_mask:0xf bank_mask:0xf
	v_fmac_f32_dpp v133, v57, v187 row_shl:15 row_mask:0xf bank_mask:0xf
	v_fmac_f32_dpp v134, v58, v188 row_shl:15 row_mask:0xf bank_mask:0xf
	v_fmac_f32_dpp v135, v59, v189 row_shl:15 row_mask:0xf bank_mask:0xf
	v_fmac_f32_dpp v136, v40, v202 row_shl:15 row_mask:0xf bank_mask:0xf
	v_fmac_f32_dpp v137, v41, v203 row_shl:15 row_mask:0xf bank_mask:0xf
	v_fmac_f32_dpp v138, v42, v204 row_shl:15 row_mask:0xf bank_mask:0xf
	v_fmac_f32_dpp v139, v43, v205 row_shl:15 row_mask:0xf bank_mask:0xf
	v_fmac_f32_dpp v132, v44, v182 row_shr:2 row_mask:0xf bank_mask:0xf
	v_fmac_f32_dpp v133, v45, v183 row_shr:2 row_mask:0xf bank_mask:0xf
	v_fmac_f32_dpp v134, v46, v184 row_shr:2 row_mask:0xf bank_mask:0xf
	v_fmac_f32_dpp v135, v47, v185 row_shr:2 row_mask:0xf bank_mask:0xf
	v_fmac_f32_dpp v136, v24, v198 row_shr:2 row_mask:0xf bank_mask:0xf
	v_fmac_f32_dpp v137, v25, v199 row_shr:2 row_mask:0xf bank_mask:0xf
	v_fmac_f32_dpp v138, v26, v200 row_shr:2 row_mask:0xf bank_mask:0xf
	v_fmac_f32_dpp v139, v27, v201 row_shr:2 row_mask:0xf bank_mask:0xf
	v_fmac_f32_dpp v132, v56, v182 row_shl:14 row_mask:0xf bank_mask:0xf
	v_fmac_f32_dpp v133, v57, v183 row_shl:14 row_mask:0xf bank_mask:0xf
	v_fmac_f32_dpp v134, v58, v184 row_shl:14 row_mask:0xf bank_mask:0xf
	v_fmac_f32_dpp v135, v59, v185 row_shl:14 row_mask:0xf bank_mask:0xf
	v_fmac_f32_dpp v136, v40, v198 row_shl:14 row_mask:0xf bank_mask:0xf
	v_fmac_f32_dpp v137, v41, v199 row_shl:14 row_mask:0xf bank_mask:0xf
	v_fmac_f32_dpp v138, v42, v200 row_shl:14 row_mask:0xf bank_mask:0xf
	v_fmac_f32_dpp v139, v43, v201 row_shl:14 row_mask:0xf bank_mask:0xf
	v_pk_mul_f32 v[140:141], v[132:133], v[132:133]
	v_pk_mul_f32 v[142:143], v[134:135], v[134:135]
	v_pk_fma_f32 v[140:141], v[140:141], s[98:99], v[244:245]
	v_pk_fma_f32 v[142:143], v[142:143], s[98:99], v[244:245]
	v_pk_mul_f32 v[140:141], v[132:133], v[140:141]
	v_pk_mul_f32 v[142:143], v[134:135], v[142:143]
	v_exp_f32_e32 v140, v140
	v_exp_f32_e32 v141, v141
	v_exp_f32_e32 v142, v142
	v_exp_f32_e32 v143, v143
	v_pk_add_f32 v[140:141], v[140:141], s[100:101]
	v_pk_add_f32 v[142:143], v[142:143], s[100:101]
	v_rcp_f32_e32 v140, v140
	v_rcp_f32_e32 v141, v141
	v_rcp_f32_e32 v142, v142
	v_rcp_f32_e32 v143, v143
	v_pk_mul_f32 v[140:141], v[132:133], v[140:141]
	v_pk_mul_f32 v[142:143], v[134:135], v[142:143]
	v_pk_mul_f32 v[140:141], v[140:141], v[136:137]
	v_pk_mul_f32 v[142:143], v[142:143], v[138:139]
	v_cvt_pk_bf16_f32 v252, v140, v141
	v_cvt_pk_bf16_f32 v253, v142, v143
	v_add_u32_e32 v144, 0x90, v248
	v_mad_u64_u32 v[144:145], vcc, v144, s4, v[242:243]
	global_store_dwordx4 v[144:145], v[250:253], off
	v_pk_fma_f32 v[132:133], v[36:37], v[158:159], v[146:147]
	v_pk_fma_f32 v[136:137], v[16:17], v[174:175], v[162:163]
	v_pk_fma_f32 v[134:135], v[38:39], v[160:161], v[148:149]
	v_pk_fma_f32 v[138:139], v[18:19], v[176:177], v[164:165]
	v_fmac_f32_dpp v132, v36, v154 row_shr:1 row_mask:0xf bank_mask:0xf
	v_fmac_f32_dpp v133, v37, v155 row_shr:1 row_mask:0xf bank_mask:0xf
	v_fmac_f32_dpp v134, v38, v156 row_shr:1 row_mask:0xf bank_mask:0xf
	v_fmac_f32_dpp v135, v39, v157 row_shr:1 row_mask:0xf bank_mask:0xf
	v_fmac_f32_dpp v136, v16, v170 row_shr:1 row_mask:0xf bank_mask:0xf
	v_fmac_f32_dpp v137, v17, v171 row_shr:1 row_mask:0xf bank_mask:0xf
	v_fmac_f32_dpp v138, v18, v172 row_shr:1 row_mask:0xf bank_mask:0xf
	v_fmac_f32_dpp v139, v19, v173 row_shr:1 row_mask:0xf bank_mask:0xf
	v_fmac_f32_dpp v132, v52, v154 row_shl:15 row_mask:0xf bank_mask:0xf
	v_fmac_f32_dpp v133, v53, v155 row_shl:15 row_mask:0xf bank_mask:0xf
	v_fmac_f32_dpp v134, v54, v156 row_shl:15 row_mask:0xf bank_mask:0xf
	v_fmac_f32_dpp v135, v55, v157 row_shl:15 row_mask:0xf bank_mask:0xf
	v_fmac_f32_dpp v136, v32, v170 row_shl:15 row_mask:0xf bank_mask:0xf
	v_fmac_f32_dpp v137, v33, v171 row_shl:15 row_mask:0xf bank_mask:0xf
	v_fmac_f32_dpp v138, v34, v172 row_shl:15 row_mask:0xf bank_mask:0xf
	v_fmac_f32_dpp v139, v35, v173 row_shl:15 row_mask:0xf bank_mask:0xf
	v_fmac_f32_dpp v132, v36, v150 row_shr:2 row_mask:0xf bank_mask:0xf
	v_fmac_f32_dpp v133, v37, v151 row_shr:2 row_mask:0xf bank_mask:0xf
	v_fmac_f32_dpp v134, v38, v152 row_shr:2 row_mask:0xf bank_mask:0xf
	v_fmac_f32_dpp v135, v39, v153 row_shr:2 row_mask:0xf bank_mask:0xf
	v_fmac_f32_dpp v136, v16, v166 row_shr:2 row_mask:0xf bank_mask:0xf
	v_fmac_f32_dpp v137, v17, v167 row_shr:2 row_mask:0xf bank_mask:0xf
	v_fmac_f32_dpp v138, v18, v168 row_shr:2 row_mask:0xf bank_mask:0xf
	v_fmac_f32_dpp v139, v19, v169 row_shr:2 row_mask:0xf bank_mask:0xf
	v_fmac_f32_dpp v132, v52, v150 row_shl:14 row_mask:0xf bank_mask:0xf
	v_fmac_f32_dpp v133, v53, v151 row_shl:14 row_mask:0xf bank_mask:0xf
	v_fmac_f32_dpp v134, v54, v152 row_shl:14 row_mask:0xf bank_mask:0xf
	v_fmac_f32_dpp v135, v55, v153 row_shl:14 row_mask:0xf bank_mask:0xf
	v_fmac_f32_dpp v136, v32, v166 row_shl:14 row_mask:0xf bank_mask:0xf
	v_fmac_f32_dpp v137, v33, v167 row_shl:14 row_mask:0xf bank_mask:0xf
	v_fmac_f32_dpp v138, v34, v168 row_shl:14 row_mask:0xf bank_mask:0xf
	v_fmac_f32_dpp v139, v35, v169 row_shl:14 row_mask:0xf bank_mask:0xf
	v_pk_mul_f32 v[140:141], v[132:133], v[132:133]
	v_pk_mul_f32 v[142:143], v[134:135], v[134:135]
	v_pk_fma_f32 v[140:141], v[140:141], s[98:99], v[244:245]
	v_pk_fma_f32 v[142:143], v[142:143], s[98:99], v[244:245]
	v_pk_mul_f32 v[140:141], v[132:133], v[140:141]
; __device__ __forceinline__ unsigned pk2(float lo, float hi) { unsigned r; asm("v_cvt_pk_bf16_f32 %0, %1, %2" : "=v"(r) : "v"(lo), "v"(hi)); return r; }
; __device__ __forceinline__ float gelu_tanh(float x) { const float y = 1.5957691216f * (x + 0.044715f * x * x * x); return x * __builtin_amdgcn_rcpf(1.0f + __expf(-y)); }
;     __device__ __forceinline__ void operator()(const f32x4 (&acc)[2][2][4][2], const Unit& u, int wr, int wc, int fr, int fq) const {
;     ...
;         for (int n = 0; n < 2; ++n) {
;             asm volatile("" ::: "memory");
;             const int jc = j0 + 4 * n;
;             const f32x4 wg0 = *(const f32x4*)(wconv + jc), wg1 = *(const f32x4*)(wconv + 2 * DFF + jc), wg2 = *(const f32x4*)(wconv + 4 * DFF + jc), bg = *(const f32x4*)(bconv + jc);
;             const f32x4 wv0 = *(const f32x4*)(wconv + DFF + jc), wv1 = *(const f32x4*)(wconv + 3 * DFF + jc), wv2 = *(const f32x4*)(wconv + 5 * DFF + jc), bv = *(const f32x4*)(bconv + DFF + jc);
; #pragma unroll
;             for (int ai = 0; ai < 2; ++ai)
; #pragma unroll
;                 for (int m = 0; m < 4; ++m) { const int row = row0 + ai * HALF + m * 16;
;                     const f32x4 g0 = acc[ai][0][m][n], v0 = acc[ai][1][m][n];
;                     f32x4 gp = (f32x4){0.f, 0.f, 0.f, 0.f}, vp = gp;
;                     if (m > 0) { gp = acc[ai][0][m > 0 ? m - 1 : 0][n]; vp = acc[ai][1][m > 0 ? m - 1 : 0][n]; }
;                     f32x4 f;
; #pragma unroll
;                     for (int j = 0; j < 4; ++j) {
;                         const float g1 = dpp_shr1(dpp_ror1(gp[j]), g0[j]), g2 = dpp_shr2(dpp_ror2(gp[j]), g0[j]);
;                         const float v1 = dpp_shr1(dpp_ror1(vp[j]), v0[j]), v2 = dpp_shr2(dpp_ror2(vp[j]), v0[j]);
;                         const float cg_ = bg[j] + g2 * wg0[j] + g1 * wg1[j] + g0[j] * wg2[j];
;                         const float cv_ = bv[j] + v2 * wv0[j] + v1 * wv1[j] + v0[j] * wv2[j];
;                         f[j] = gelu_tanh(cg_) * cv_; }
;                     u32x2 w; w.x = pk2(f[0], f[1]); w.y = pk2(f[2], f[3]);
;                     if (n == 0) res0[ai * 4 + m] = w;
;                     else if (m > 0 || fr >= 2) { u32x4 w4; w4.x = res0[ai * 4 + m].x; w4.y = res0[ai * 4 + m].y; w4.z = w.x; w4.w = w.y; *(u32x4*)(F + (size_t)row * DFF + j0) = w4; }
	v_pk_mul_f32 v[142:143], v[134:135], v[142:143]
	v_exp_f32_e32 v140, v140
	v_exp_f32_e32 v141, v141
	v_exp_f32_e32 v142, v142
	v_exp_f32_e32 v143, v143
	v_pk_add_f32 v[140:141], v[140:141], s[100:101]
	v_pk_add_f32 v[142:143], v[142:143], s[100:101]
	v_rcp_f32_e32 v140, v140
	v_rcp_f32_e32 v141, v141
	v_rcp_f32_e32 v142, v142
	v_rcp_f32_e32 v143, v143
	v_pk_mul_f32 v[140:141], v[132:133], v[140:141]
	v_pk_mul_f32 v[142:143], v[134:135], v[142:143]
	v_pk_mul_f32 v[140:141], v[140:141], v[136:137]
	v_pk_mul_f32 v[142:143], v[142:143], v[138:139]
	v_cvt_pk_bf16_f32 v128, v140, v141
	v_cvt_pk_bf16_f32 v129, v142, v143
	v_pk_fma_f32 v[132:133], v[28:29], v[190:191], v[178:179]
	v_pk_fma_f32 v[136:137], v[8:9], v[206:207], v[194:195]
	v_pk_fma_f32 v[134:135], v[30:31], v[192:193], v[180:181]
	v_pk_fma_f32 v[138:139], v[10:11], v[208:209], v[196:197]
	v_fmac_f32_dpp v132, v28, v186 row_shr:1 row_mask:0xf bank_mask:0xf
	v_fmac_f32_dpp v133, v29, v187 row_shr:1 row_mask:0xf bank_mask:0xf
	v_fmac_f32_dpp v134, v30, v188 row_shr:1 row_mask:0xf bank_mask:0xf
	v_fmac_f32_dpp v135, v31, v189 row_shr:1 row_mask:0xf bank_mask:0xf
	v_fmac_f32_dpp v136, v8, v202 row_shr:1 row_mask:0xf bank_mask:0xf
	v_fmac_f32_dpp v137, v9, v203 row_shr:1 row_mask:0xf bank_mask:0xf
	v_fmac_f32_dpp v138, v10, v204 row_shr:1 row_mask:0xf bank_mask:0xf
	v_fmac_f32_dpp v139, v11, v205 row_shr:1 row_mask:0xf bank_mask:0xf
	v_fmac_f32_dpp v132, v44, v186 row_shl:15 row_mask:0xf bank_mask:0xf
	v_fmac_f32_dpp v133, v45, v187 row_shl:15 row_mask:0xf bank_mask:0xf
	v_fmac_f32_dpp v134, v46, v188 row_shl:15 row_mask:0xf bank_mask:0xf
	v_fmac_f32_dpp v135, v47, v189 row_shl:15 row_mask:0xf bank_mask:0xf
	v_fmac_f32_dpp v136, v24, v202 row_shl:15 row_mask:0xf bank_mask:0xf
	v_fmac_f32_dpp v137, v25, v203 row_shl:15 row_mask:0xf bank_mask:0xf
	v_fmac_f32_dpp v138, v26, v204 row_shl:15 row_mask:0xf bank_mask:0xf
	v_fmac_f32_dpp v139, v27, v205 row_shl:15 row_mask:0xf bank_mask:0xf
	v_fmac_f32_dpp v132, v28, v182 row_shr:2 row_mask:0xf bank_mask:0xf
	v_fmac_f32_dpp v133, v29, v183 row_shr:2 row_mask:0xf bank_mask:0xf
	v_fmac_f32_dpp v134, v30, v184 row_shr:2 row_mask:0xf bank_mask:0xf
	v_fmac_f32_dpp v135, v31, v185 row_shr:2 row_mask:0xf bank_mask:0xf
	v_fmac_f32_dpp v136, v8, v198 row_shr:2 row_mask:0xf bank_mask:0xf
	v_fmac_f32_dpp v137, v9, v199 row_shr:2 row_mask:0xf bank_mask:0xf
	v_fmac_f32_dpp v138, v10, v200 row_shr:2 row_mask:0xf bank_mask:0xf
	v_fmac_f32_dpp v139, v11, v201 row_shr:2 row_mask:0xf bank_mask:0xf
	v_fmac_f32_dpp v132, v44, v182 row_shl:14 row_mask:0xf bank_mask:0xf
	v_fmac_f32_dpp v133, v45, v183 row_shl:14 row_mask:0xf bank_mask:0xf
	v_fmac_f32_dpp v134, v46, v184 row_shl:14 row_mask:0xf bank_mask:0xf
	v_fmac_f32_dpp v135, v47, v185 row_shl:14 row_mask:0xf bank_mask:0xf
	v_fmac_f32_dpp v136, v24, v198 row_shl:14 row_mask:0xf bank_mask:0xf
	v_fmac_f32_dpp v137, v25, v199 row_shl:14 row_mask:0xf bank_mask:0xf
	v_fmac_f32_dpp v138, v26, v200 row_shl:14 row_mask:0xf bank_mask:0xf
	v_fmac_f32_dpp v139, v27, v201 row_shl:14 row_mask:0xf bank_mask:0xf
	v_pk_mul_f32 v[140:141], v[132:133], v[132:133]
	v_pk_mul_f32 v[142:143], v[134:135], v[134:135]
	v_pk_fma_f32 v[140:141], v[140:141], s[98:99], v[244:245]
	v_pk_fma_f32 v[142:143], v[142:143], s[98:99], v[244:245]
	v_pk_mul_f32 v[140:141], v[132:133], v[140:141]
	v_pk_mul_f32 v[142:143], v[134:135], v[142:143]
	v_exp_f32_e32 v140, v140
	v_exp_f32_e32 v141, v141
	v_exp_f32_e32 v142, v142
	v_exp_f32_e32 v143, v143
	v_pk_add_f32 v[140:141], v[140:141], s[100:101]
	v_pk_add_f32 v[142:143], v[142:143], s[100:101]
	v_rcp_f32_e32 v140, v140
	v_rcp_f32_e32 v141, v141
	v_rcp_f32_e32 v142, v142
	v_rcp_f32_e32 v143, v143
	v_pk_mul_f32 v[140:141], v[132:133], v[140:141]
	v_pk_mul_f32 v[142:143], v[134:135], v[142:143]
	v_pk_mul_f32 v[140:141], v[140:141], v[136:137]
	v_pk_mul_f32 v[142:143], v[142:143], v[138:139]
	v_cvt_pk_bf16_f32 v130, v140, v141
	v_cvt_pk_bf16_f32 v131, v142, v143
	v_add_u32_e32 v144, 0xa0, v248
	v_mad_u64_u32 v[144:145], vcc, v144, s4, v[242:243]
	global_store_dwordx4 v[144:145], v[128:131], off
	v_pk_fma_f32 v[132:133], v[20:21], v[158:159], v[146:147]
	v_pk_fma_f32 v[136:137], v[4:5], v[174:175], v[162:163]
	v_pk_fma_f32 v[134:135], v[22:23], v[160:161], v[148:149]
	v_pk_fma_f32 v[138:139], v[6:7], v[176:177], v[164:165]
	v_fmac_f32_dpp v132, v20, v154 row_shr:1 row_mask:0xf bank_mask:0xf
	v_fmac_f32_dpp v133, v21, v155 row_shr:1 row_mask:0xf bank_mask:0xf
	v_fmac_f32_dpp v134, v22, v156 row_shr:1 row_mask:0xf bank_mask:0xf
	v_fmac_f32_dpp v135, v23, v157 row_shr:1 row_mask:0xf bank_mask:0xf
	v_fmac_f32_dpp v136, v4, v170 row_shr:1 row_mask:0xf bank_mask:0xf
	v_fmac_f32_dpp v137, v5, v171 row_shr:1 row_mask:0xf bank_mask:0xf
	v_fmac_f32_dpp v138, v6, v172 row_shr:1 row_mask:0xf bank_mask:0xf
	v_fmac_f32_dpp v139, v7, v173 row_shr:1 row_mask:0xf bank_mask:0xf
	v_fmac_f32_dpp v132, v36, v154 row_shl:15 row_mask:0xf bank_mask:0xf
	v_fmac_f32_dpp v133, v37, v155 row_shl:15 row_mask:0xf bank_mask:0xf
	v_fmac_f32_dpp v134, v38, v156 row_shl:15 row_mask:0xf bank_mask:0xf
	v_fmac_f32_dpp v135, v39, v157 row_shl:15 row_mask:0xf bank_mask:0xf
	v_fmac_f32_dpp v136, v16, v170 row_shl:15 row_mask:0xf bank_mask:0xf
	v_fmac_f32_dpp v137, v17, v171 row_shl:15 row_mask:0xf bank_mask:0xf
	v_fmac_f32_dpp v138, v18, v172 row_shl:15 row_mask:0xf bank_mask:0xf
	v_fmac_f32_dpp v139, v19, v173 row_shl:15 row_mask:0xf bank_mask:0xf
	v_fmac_f32_dpp v132, v20, v150 row_shr:2 row_mask:0xf bank_mask:0xf
	v_fmac_f32_dpp v133, v21, v151 row_shr:2 row_mask:0xf bank_mask:0xf
	v_fmac_f32_dpp v134, v22, v152 row_shr:2 row_mask:0xf bank_mask:0xf
; __device__ __forceinline__ unsigned pk2(float lo, float hi) { unsigned r; asm("v_cvt_pk_bf16_f32 %0, %1, %2" : "=v"(r) : "v"(lo), "v"(hi)); return r; }
; __device__ __forceinline__ float gelu_tanh(float x) { const float y = 1.5957691216f * (x + 0.044715f * x * x * x); return x * __builtin_amdgcn_rcpf(1.0f + __expf(-y)); }
; __device__ __forceinline__ float dpp_shr1(float old, float src) { return __int_as_float(__builtin_amdgcn_update_dpp(__float_as_int(old), __float_as_int(src), 0x111, 0xf, 0xf, false)); }
;     __device__ __forceinline__ void operator()(const f32x4 (&acc)[2][2][4][2], const Unit& u, int wr, int wc, int fr, int fq) const {
;     ...
;                     if (m > 0) { gp = acc[ai][0][m > 0 ? m - 1 : 0][n]; vp = acc[ai][1][m > 0 ? m - 1 : 0][n]; }
;                     f32x4 f;
; #pragma unroll
;                     for (int j = 0; j < 4; ++j) {
;                         const float g1 = dpp_shr1(dpp_ror1(gp[j]), g0[j]), g2 = dpp_shr2(dpp_ror2(gp[j]), g0[j]);
;                         const float v1 = dpp_shr1(dpp_ror1(vp[j]), v0[j]), v2 = dpp_shr2(dpp_ror2(vp[j]), v0[j]);
;                         const float cg_ = bg[j] + g2 * wg0[j] + g1 * wg1[j] + g0[j] * wg2[j];
;                         const float cv_ = bv[j] + v2 * wv0[j] + v1 * wv1[j] + v0[j] * wv2[j];
;                         f[j] = gelu_tanh(cg_) * cv_; }
;                     u32x2 w; w.x = pk2(f[0], f[1]); w.y = pk2(f[2], f[3]);
;                     if (n == 0) res0[ai * 4 + m] = w;
;                     else if (m > 0 || fr >= 2) { u32x4 w4; w4.x = res0[ai * 4 + m].x; w4.y = res0[ai * 4 + m].y; w4.z = w.x; w4.w = w.y; *(u32x4*)(F + (size_t)row * DFF + j0) = w4; }
;                     if (n == 1 && ((m == 0 && fr < 2) || (m == 3 && fr >= 14))) { const int slot = m == 0 ? fr : fr - 12;
;                         const f32x4 ga = acc[ai][0][m][0], va = acc[ai][1][m][0];
;                         bf16_t* bp = UPB + ((size_t)(row >> 6) * 4 + slot) * (2 * DFF) + col0;
;                         u32x4 wg_, wv_; wg_.x = pk2(ga[0], ga[1]); wg_.y = pk2(ga[2], ga[3]); wg_.z = pk2(g0[0], g0[1]); wg_.w = pk2(g0[2], g0[3]);
;                         wv_.x = pk2(va[0], va[1]); wv_.y = pk2(va[2], va[3]); wv_.z = pk2(v0[0], v0[1]); wv_.w = pk2(v0[2], v0[3]);
;                         *(u32x4*)bp = wg_; *(u32x4*)(bp + HALF) = wv_; } }
	v_fmac_f32_dpp v135, v23, v153 row_shr:2 row_mask:0xf bank_mask:0xf
	v_fmac_f32_dpp v136, v4, v166 row_shr:2 row_mask:0xf bank_mask:0xf
	v_fmac_f32_dpp v137, v5, v167 row_shr:2 row_mask:0xf bank_mask:0xf
	v_fmac_f32_dpp v138, v6, v168 row_shr:2 row_mask:0xf bank_mask:0xf
	v_fmac_f32_dpp v139, v7, v169 row_shr:2 row_mask:0xf bank_mask:0xf
	v_fmac_f32_dpp v132, v36, v150 row_shl:14 row_mask:0xf bank_mask:0xf
	v_fmac_f32_dpp v133, v37, v151 row_shl:14 row_mask:0xf bank_mask:0xf
	v_fmac_f32_dpp v134, v38, v152 row_shl:14 row_mask:0xf bank_mask:0xf
	v_fmac_f32_dpp v135, v39, v153 row_shl:14 row_mask:0xf bank_mask:0xf
	v_fmac_f32_dpp v136, v16, v166 row_shl:14 row_mask:0xf bank_mask:0xf
	v_fmac_f32_dpp v137, v17, v167 row_shl:14 row_mask:0xf bank_mask:0xf
	v_fmac_f32_dpp v138, v18, v168 row_shl:14 row_mask:0xf bank_mask:0xf
	v_fmac_f32_dpp v139, v19, v169 row_shl:14 row_mask:0xf bank_mask:0xf
	v_pk_mul_f32 v[140:141], v[132:133], v[132:133]
	v_pk_mul_f32 v[142:143], v[134:135], v[134:135]
	v_pk_fma_f32 v[140:141], v[140:141], s[98:99], v[244:245]
	v_pk_fma_f32 v[142:143], v[142:143], s[98:99], v[244:245]
	v_pk_mul_f32 v[140:141], v[132:133], v[140:141]
	v_pk_mul_f32 v[142:143], v[134:135], v[142:143]
	v_exp_f32_e32 v140, v140
	v_exp_f32_e32 v141, v141
	v_exp_f32_e32 v142, v142
	v_exp_f32_e32 v143, v143
	v_pk_add_f32 v[140:141], v[140:141], s[100:101]
	v_pk_add_f32 v[142:143], v[142:143], s[100:101]
	v_rcp_f32_e32 v140, v140
	v_rcp_f32_e32 v141, v141
	v_rcp_f32_e32 v142, v142
	v_rcp_f32_e32 v143, v143
	v_pk_mul_f32 v[140:141], v[132:133], v[140:141]
	v_pk_mul_f32 v[142:143], v[134:135], v[142:143]
	v_pk_mul_f32 v[140:141], v[140:141], v[136:137]
	v_pk_mul_f32 v[142:143], v[142:143], v[138:139]
	v_cvt_pk_bf16_f32 v250, v140, v141
	v_cvt_pk_bf16_f32 v251, v142, v143
	v_pk_fma_f32 v[132:133], v[12:13], v[190:191], v[178:179]
	v_pk_fma_f32 v[136:137], v[0:1], v[206:207], v[194:195]
	v_pk_fma_f32 v[134:135], v[14:15], v[192:193], v[180:181]
	v_pk_fma_f32 v[138:139], v[2:3], v[208:209], v[196:197]
	v_fmac_f32_dpp v132, v12, v186 row_shr:1 row_mask:0xf bank_mask:0xf
	v_fmac_f32_dpp v133, v13, v187 row_shr:1 row_mask:0xf bank_mask:0xf
	v_fmac_f32_dpp v134, v14, v188 row_shr:1 row_mask:0xf bank_mask:0xf
	v_fmac_f32_dpp v135, v15, v189 row_shr:1 row_mask:0xf bank_mask:0xf
	v_fmac_f32_dpp v136, v0, v202 row_shr:1 row_mask:0xf bank_mask:0xf
	v_fmac_f32_dpp v137, v1, v203 row_shr:1 row_mask:0xf bank_mask:0xf
	v_fmac_f32_dpp v138, v2, v204 row_shr:1 row_mask:0xf bank_mask:0xf
	v_fmac_f32_dpp v139, v3, v205 row_shr:1 row_mask:0xf bank_mask:0xf
	v_fmac_f32_dpp v132, v28, v186 row_shl:15 row_mask:0xf bank_mask:0xf
	v_fmac_f32_dpp v133, v29, v187 row_shl:15 row_mask:0xf bank_mask:0xf
	v_fmac_f32_dpp v134, v30, v188 row_shl:15 row_mask:0xf bank_mask:0xf
	v_fmac_f32_dpp v135, v31, v189 row_shl:15 row_mask:0xf bank_mask:0xf
	v_fmac_f32_dpp v136, v8, v202 row_shl:15 row_mask:0xf bank_mask:0xf
	v_fmac_f32_dpp v137, v9, v203 row_shl:15 row_mask:0xf bank_mask:0xf
	v_fmac_f32_dpp v138, v10, v204 row_shl:15 row_mask:0xf bank_mask:0xf
	v_fmac_f32_dpp v139, v11, v205 row_shl:15 row_mask:0xf bank_mask:0xf
	v_fmac_f32_dpp v132, v12, v182 row_shr:2 row_mask:0xf bank_mask:0xf
	v_fmac_f32_dpp v133, v13, v183 row_shr:2 row_mask:0xf bank_mask:0xf
	v_fmac_f32_dpp v134, v14, v184 row_shr:2 row_mask:0xf bank_mask:0xf
	v_fmac_f32_dpp v135, v15, v185 row_shr:2 row_mask:0xf bank_mask:0xf
	v_fmac_f32_dpp v136, v0, v198 row_shr:2 row_mask:0xf bank_mask:0xf
	v_fmac_f32_dpp v137, v1, v199 row_shr:2 row_mask:0xf bank_mask:0xf
	v_fmac_f32_dpp v138, v2, v200 row_shr:2 row_mask:0xf bank_mask:0xf
	v_fmac_f32_dpp v139, v3, v201 row_shr:2 row_mask:0xf bank_mask:0xf
	v_fmac_f32_dpp v132, v28, v182 row_shl:14 row_mask:0xf bank_mask:0xf
	v_fmac_f32_dpp v133, v29, v183 row_shl:14 row_mask:0xf bank_mask:0xf
	v_fmac_f32_dpp v134, v30, v184 row_shl:14 row_mask:0xf bank_mask:0xf
	v_fmac_f32_dpp v135, v31, v185 row_shl:14 row_mask:0xf bank_mask:0xf
	v_fmac_f32_dpp v136, v8, v198 row_shl:14 row_mask:0xf bank_mask:0xf
	v_fmac_f32_dpp v137, v9, v199 row_shl:14 row_mask:0xf bank_mask:0xf
	v_fmac_f32_dpp v138, v10, v200 row_shl:14 row_mask:0xf bank_mask:0xf
	v_fmac_f32_dpp v139, v11, v201 row_shl:14 row_mask:0xf bank_mask:0xf
	v_pk_mul_f32 v[140:141], v[132:133], v[132:133]
	v_pk_mul_f32 v[142:143], v[134:135], v[134:135]
	v_pk_fma_f32 v[140:141], v[140:141], s[98:99], v[244:245]
	v_pk_fma_f32 v[142:143], v[142:143], s[98:99], v[244:245]
	v_pk_mul_f32 v[140:141], v[132:133], v[140:141]
	v_pk_mul_f32 v[142:143], v[134:135], v[142:143]
	v_exp_f32_e32 v140, v140
	v_exp_f32_e32 v141, v141
	v_exp_f32_e32 v142, v142
	v_exp_f32_e32 v143, v143
	v_pk_add_f32 v[140:141], v[140:141], s[100:101]
	v_pk_add_f32 v[142:143], v[142:143], s[100:101]
	v_rcp_f32_e32 v140, v140
	v_rcp_f32_e32 v141, v141
	v_rcp_f32_e32 v142, v142
	v_rcp_f32_e32 v143, v143
	v_pk_mul_f32 v[140:141], v[132:133], v[140:141]
	v_pk_mul_f32 v[142:143], v[134:135], v[142:143]
	v_pk_mul_f32 v[140:141], v[140:141], v[136:137]
	v_pk_mul_f32 v[142:143], v[142:143], v[138:139]
	v_cvt_pk_bf16_f32 v252, v140, v141
	v_cvt_pk_bf16_f32 v253, v142, v143
	v_add_u32_e32 v144, 0xb0, v248
	v_mad_u64_u32 v[144:145], vcc, v144, s4, v[242:243]
	global_store_dwordx4 v[144:145], v[250:253], off
	s_mov_b64 s[0:1], 0
	s_and_saveexec_b64 s[42:43], s[12:13]
	s_xor_b64 s[52:53], exec, s[42:43]
	s_cbranch_execz .LBB0_1214
	v_add_u32_e32 v144, s73, v234
	v_mov_b64_e32 v[132:133], s[80:81]
	v_mad_u64_u32 v[132:133], vcc, v144, s83, v[132:133]
	v_lshl_add_u64 v[132:133], v[240:241], 1, v[132:133]
	s_mov_b64 s[72:73], exec
	v_cvt_pk_bf16_f32 v134, v20, v21
	v_cvt_pk_bf16_f32 v135, v22, v23
	v_cvt_pk_bf16_f32 v136, v12, v13
	v_cvt_pk_bf16_f32 v137, v14, v15
	v_cvt_pk_bf16_f32 v128, v4, v5
	v_cvt_pk_bf16_f32 v129, v6, v7
	v_cvt_pk_bf16_f32 v130, v0, v1
	v_cvt_pk_bf16_f32 v131, v2, v3
	global_store_dwordx4 v[132:133], v[134:137], off
